# plus RWKV scan: DPP butterfly levels fused into v_add_f32_dpp pairs (79 sites)
# speedup vs baseline: 1.0018x; 1.0018x over previous
.LBB0_595:
	s_andn2_saveexec_b64 s[0:1], s[20:21]
	s_cbranch_execz .LBB0_609
	s_bitcmp1_b32 s25, 0
	s_cselect_b32 s20, 0x6000, 0
	v_add_u32_e32 v1, s20, v143
	ds_read_b128 v[32:35], v1
	ds_read_b128 v[40:43], v1 offset:16
	s_and_b32 s20, s25, 1
	s_mul_i32 s21, s20, 0x6000
	s_add_i32 s21, s21, 0
	s_waitcnt lgkmcnt(1)
	v_pk_mul_f32 v[2:3], v[66:67], v[34:35] op_sel_hi:[1,0]
	v_pk_mul_f32 v[34:35], v[64:65], v[34:35] op_sel:[0,1]
	v_pk_fma_f32 v[2:3], v[70:71], v[32:33], v[2:3] op_sel_hi:[1,0,1]
	v_pk_fma_f32 v[32:33], v[68:69], v[32:33], v[34:35] op_sel:[0,1,0]
	s_waitcnt lgkmcnt(0)
	v_pk_fma_f32 v[2:3], v[62:63], v[40:41], v[2:3] op_sel_hi:[1,0,1]
	v_pk_fma_f32 v[32:33], v[60:61], v[40:41], v[32:33] op_sel:[0,1,0]
	v_pk_fma_f32 v[2:3], v[46:47], v[42:43], v[2:3] op_sel_hi:[1,0,1]
	v_pk_fma_f32 v[32:33], v[44:45], v[42:43], v[32:33] op_sel:[0,1,0]
	v_lshl_add_u32 v152, v97, 2, s21
	v_pk_add_f32 v[2:3], v[2:3], v[32:33]
	v_lshl_add_u32 v151, v98, 2, s21
	ds_read_b128 v[72:75], v152 offset:4096
	ds_read_b128 v[154:157], v152 offset:4112
	ds_read_b128 v[158:161], v152 offset:8192
	ds_read_b128 v[166:169], v152 offset:8208
	ds_read_b128 v[170:173], v152 offset:12288
	ds_read_b128 v[174:177], v152 offset:12304
	ds_read_b128 v[178:181], v152 offset:16384
	ds_read_b128 v[198:201], v152 offset:16400
	ds_read_b64 v[202:203], v151 offset:20480
	ds_read_b128 v[36:39], v1 offset:256
	ds_read_b128 v[28:31], v1 offset:272
	v_add_f32_dpp v2, v2, v2 quad_perm:[1,0,3,2] row_mask:0xf bank_mask:0xf bound_ctrl:1
	v_add_f32_dpp v3, v3, v3 quad_perm:[1,0,3,2] row_mask:0xf bank_mask:0xf bound_ctrl:1
	s_lshl_b32 s20, s20, 12
	v_add_u32_e32 v153, s20, v99
	v_add_f32_dpp v2, v2, v2 quad_perm:[2,3,0,1] row_mask:0xf bank_mask:0xf bound_ctrl:1
	v_add_f32_dpp v3, v3, v3 quad_perm:[2,3,0,1] row_mask:0xf bank_mask:0xf bound_ctrl:1
	s_nop 0
	v_add_f32_dpp v32, v2, v2 row_half_mirror row_mask:0xf bank_mask:0xf bound_ctrl:1
	v_add_f32_dpp v33, v3, v3 row_half_mirror row_mask:0xf bank_mask:0xf bound_ctrl:1
	s_waitcnt lgkmcnt(8)
	v_pk_mul_f32 v[2:3], v[158:159], v[32:33] op_sel_hi:[0,1]
	s_waitcnt lgkmcnt(2)
	v_pk_fma_f32 v[2:3], v[170:171], v[202:203], v[2:3] op_sel_hi:[0,1,1] neg_lo:[0,0,1] neg_hi:[0,0,1]
	v_pk_mul_f32 v[34:35], v[158:159], v[32:33] op_sel:[1,0]
	v_pk_fma_f32 v[2:3], v[70:71], v[72:73], v[2:3] op_sel_hi:[1,0,1]
	v_pk_fma_f32 v[34:35], v[170:171], v[202:203], v[34:35] op_sel:[1,0,0] neg_lo:[0,0,1] neg_hi:[0,0,1]
	v_pk_mul_f32 v[42:43], v[160:161], v[32:33] op_sel_hi:[0,1]
	v_pk_fma_f32 v[68:69], v[68:69], v[72:73], v[34:35] op_sel:[0,1,0]
	v_pk_fma_f32 v[42:43], v[172:173], v[202:203], v[42:43] op_sel_hi:[0,1,1] neg_lo:[0,0,1] neg_hi:[0,0,1]
	v_pk_mul_f32 v[70:71], v[160:161], v[32:33] op_sel:[1,0]
	v_pk_fma_f32 v[66:67], v[66:67], v[74:75], v[42:43] op_sel_hi:[1,0,1]
	v_pk_fma_f32 v[70:71], v[172:173], v[202:203], v[70:71] op_sel:[1,0,0] neg_lo:[0,0,1] neg_hi:[0,0,1]
	v_pk_fma_f32 v[40:41], v[178:179], v[68:69], 0 op_sel:[1,0,0] op_sel_hi:[1,1,0]
	v_pk_fma_f32 v[64:65], v[64:65], v[74:75], v[70:71] op_sel:[0,1,0]
	v_pk_fma_f32 v[40:41], v[180:181], v[64:65], v[40:41] op_sel:[1,0,0]
	v_pk_mul_f32 v[42:43], v[166:167], v[32:33] op_sel_hi:[0,1]
	v_pk_fma_f32 v[42:43], v[174:175], v[202:203], v[42:43] op_sel_hi:[0,1,1] neg_lo:[0,0,1] neg_hi:[0,0,1]
	v_pk_fma_f32 v[62:63], v[62:63], v[154:155], v[42:43] op_sel_hi:[1,0,1]
	v_pk_mul_f32 v[42:43], v[166:167], v[32:33] op_sel:[1,0]
	v_pk_fma_f32 v[34:35], v[178:179], v[2:3], 0 op_sel_hi:[0,1,0]
	v_pk_fma_f32 v[42:43], v[174:175], v[202:203], v[42:43] op_sel:[1,0,0] neg_lo:[0,0,1] neg_hi:[0,0,1]
	v_pk_fma_f32 v[60:61], v[60:61], v[154:155], v[42:43] op_sel:[0,1,0]
	v_pk_mul_f32 v[42:43], v[168:169], v[32:33] op_sel_hi:[0,1]
	v_pk_fma_f32 v[34:35], v[180:181], v[66:67], v[34:35] op_sel_hi:[0,1,1]
	v_pk_fma_f32 v[42:43], v[176:177], v[202:203], v[42:43] op_sel_hi:[0,1,1] neg_lo:[0,0,1] neg_hi:[0,0,1]
	v_pk_mul_f32 v[32:33], v[168:169], v[32:33] op_sel:[1,0]
	v_pk_fma_f32 v[34:35], v[198:199], v[62:63], v[34:35] op_sel_hi:[0,1,1]
	v_pk_fma_f32 v[46:47], v[46:47], v[156:157], v[42:43] op_sel_hi:[1,0,1]
	v_pk_fma_f32 v[32:33], v[176:177], v[202:203], v[32:33] op_sel:[1,0,0] neg_lo:[0,0,1] neg_hi:[0,0,1]
	v_pk_fma_f32 v[40:41], v[198:199], v[60:61], v[40:41] op_sel:[1,0,0]
	v_pk_fma_f32 v[44:45], v[44:45], v[156:157], v[32:33] op_sel:[0,1,0]
	v_pk_fma_f32 v[32:33], v[200:201], v[46:47], v[34:35] op_sel_hi:[0,1,1]
	v_pk_fma_f32 v[34:35], v[200:201], v[44:45], v[40:41] op_sel:[1,0,0]
	v_pk_add_f32 v[32:33], v[32:33], v[34:35]
	s_nop 1
	v_add_f32_dpp v32, v32, v32 quad_perm:[1,0,3,2] row_mask:0xf bank_mask:0xf bound_ctrl:1
	v_add_f32_dpp v33, v33, v33 quad_perm:[1,0,3,2] row_mask:0xf bank_mask:0xf bound_ctrl:1
	s_nop 0
	v_add_f32_dpp v32, v32, v32 quad_perm:[2,3,0,1] row_mask:0xf bank_mask:0xf bound_ctrl:1
	v_add_f32_dpp v33, v33, v33 quad_perm:[2,3,0,1] row_mask:0xf bank_mask:0xf bound_ctrl:1
	s_nop 0
	v_mov_b32_dpp v34, v32 row_half_mirror row_mask:0xf bank_mask:0xf bound_ctrl:1
	v_mov_b32_dpp v35, v33 row_half_mirror row_mask:0xf bank_mask:0xf bound_ctrl:1
	s_and_saveexec_b64 s[20:21], s[14:15]
	v_pk_add_f32 v[32:33], v[32:33], v[34:35]
	ds_write_b64 v153, v[32:33] offset:49152
	s_or_b64 exec, exec, s[20:21]
	s_waitcnt lgkmcnt(1)
	v_pk_mul_f32 v[202:203], v[38:39], v[66:67] op_sel_hi:[0,1]
	v_pk_fma_f32 v[202:203], v[36:37], v[2:3], v[202:203] op_sel_hi:[0,1,1]
	v_pk_mul_f32 v[38:39], v[38:39], v[64:65] op_sel:[1,0]
	v_pk_fma_f32 v[36:37], v[36:37], v[68:69], v[38:39] op_sel:[1,0,0]
	s_waitcnt lgkmcnt(0)
	v_pk_fma_f32 v[38:39], v[28:29], v[62:63], v[202:203] op_sel_hi:[0,1,1]
	v_pk_fma_f32 v[28:29], v[28:29], v[60:61], v[36:37] op_sel:[1,0,0]
	v_pk_fma_f32 v[36:37], v[30:31], v[46:47], v[38:39] op_sel_hi:[0,1,1]
	v_pk_fma_f32 v[28:29], v[30:31], v[44:45], v[28:29] op_sel:[1,0,0]
	v_pk_add_f32 v[28:29], v[36:37], v[28:29]
	ds_read_b128 v[70:73], v152 offset:4352
	ds_read_b128 v[154:157], v152 offset:4368
	ds_read_b128 v[158:161], v152 offset:8448
	ds_read_b128 v[166:169], v152 offset:8464
	ds_read_b128 v[170:173], v152 offset:12544
	ds_read_b128 v[174:177], v152 offset:12560
	ds_read_b128 v[178:181], v152 offset:16640
	ds_read_b128 v[198:201], v152 offset:16656
	ds_read_b64 v[74:75], v151 offset:20736
	ds_read_b128 v[40:43], v1 offset:512
	ds_read_b128 v[32:35], v1 offset:528
	v_add_f32_dpp v28, v28, v28 quad_perm:[1,0,3,2] row_mask:0xf bank_mask:0xf bound_ctrl:1
	v_add_f32_dpp v29, v29, v29 quad_perm:[1,0,3,2] row_mask:0xf bank_mask:0xf bound_ctrl:1
	s_nop 0
	v_add_f32_dpp v28, v28, v28 quad_perm:[2,3,0,1] row_mask:0xf bank_mask:0xf bound_ctrl:1
	v_add_f32_dpp v29, v29, v29 quad_perm:[2,3,0,1] row_mask:0xf bank_mask:0xf bound_ctrl:1
	s_nop 0
	v_add_f32_dpp v28, v28, v28 row_half_mirror row_mask:0xf bank_mask:0xf bound_ctrl:1
	v_add_f32_dpp v29, v29, v29 row_half_mirror row_mask:0xf bank_mask:0xf bound_ctrl:1
	s_waitcnt lgkmcnt(8)
	v_pk_mul_f32 v[30:31], v[158:159], v[28:29] op_sel_hi:[0,1]
	s_waitcnt lgkmcnt(2)
	v_pk_fma_f32 v[30:31], v[170:171], v[74:75], v[30:31] op_sel_hi:[0,1,1] neg_lo:[0,0,1] neg_hi:[0,0,1]
	v_pk_fma_f32 v[2:3], v[2:3], v[70:71], v[30:31] op_sel_hi:[1,0,1]
	v_pk_mul_f32 v[30:31], v[158:159], v[28:29] op_sel:[1,0]
	v_pk_mul_f32 v[38:39], v[160:161], v[28:29] op_sel_hi:[0,1]
	v_pk_fma_f32 v[30:31], v[170:171], v[74:75], v[30:31] op_sel:[1,0,0] neg_lo:[0,0,1] neg_hi:[0,0,1]
	v_pk_fma_f32 v[38:39], v[172:173], v[74:75], v[38:39] op_sel_hi:[0,1,1] neg_lo:[0,0,1] neg_hi:[0,0,1]
	v_pk_fma_f32 v[68:69], v[68:69], v[70:71], v[30:31] op_sel:[0,1,0]
	v_pk_fma_f32 v[66:67], v[66:67], v[72:73], v[38:39] op_sel_hi:[1,0,1]
	v_pk_mul_f32 v[70:71], v[160:161], v[28:29] op_sel:[1,0]
	v_pk_fma_f32 v[70:71], v[172:173], v[74:75], v[70:71] op_sel:[1,0,0] neg_lo:[0,0,1] neg_hi:[0,0,1]
	v_pk_fma_f32 v[36:37], v[178:179], v[68:69], 0 op_sel:[1,0,0] op_sel_hi:[1,1,0]
	v_pk_fma_f32 v[64:65], v[64:65], v[72:73], v[70:71] op_sel:[0,1,0]
	v_pk_fma_f32 v[36:37], v[180:181], v[64:65], v[36:37] op_sel:[1,0,0]
	v_pk_mul_f32 v[38:39], v[166:167], v[28:29] op_sel_hi:[0,1]
	v_pk_fma_f32 v[38:39], v[174:175], v[74:75], v[38:39] op_sel_hi:[0,1,1] neg_lo:[0,0,1] neg_hi:[0,0,1]
	v_pk_fma_f32 v[62:63], v[62:63], v[154:155], v[38:39] op_sel_hi:[1,0,1]
	v_pk_mul_f32 v[38:39], v[166:167], v[28:29] op_sel:[1,0]
	v_pk_fma_f32 v[30:31], v[178:179], v[2:3], 0 op_sel_hi:[0,1,0]
	v_pk_fma_f32 v[38:39], v[174:175], v[74:75], v[38:39] op_sel:[1,0,0] neg_lo:[0,0,1] neg_hi:[0,0,1]
	v_pk_fma_f32 v[60:61], v[60:61], v[154:155], v[38:39] op_sel:[0,1,0]
	v_pk_mul_f32 v[38:39], v[168:169], v[28:29] op_sel_hi:[0,1]
	v_pk_fma_f32 v[30:31], v[180:181], v[66:67], v[30:31] op_sel_hi:[0,1,1]
	v_pk_fma_f32 v[38:39], v[176:177], v[74:75], v[38:39] op_sel_hi:[0,1,1] neg_lo:[0,0,1] neg_hi:[0,0,1]
	v_pk_mul_f32 v[28:29], v[168:169], v[28:29] op_sel:[1,0]
	v_pk_fma_f32 v[30:31], v[198:199], v[62:63], v[30:31] op_sel_hi:[0,1,1]
	v_pk_fma_f32 v[46:47], v[46:47], v[156:157], v[38:39] op_sel_hi:[1,0,1]
	v_pk_fma_f32 v[28:29], v[176:177], v[74:75], v[28:29] op_sel:[1,0,0] neg_lo:[0,0,1] neg_hi:[0,0,1]
	v_pk_fma_f32 v[36:37], v[198:199], v[60:61], v[36:37] op_sel:[1,0,0]
	v_pk_fma_f32 v[44:45], v[44:45], v[156:157], v[28:29] op_sel:[0,1,0]
	v_pk_fma_f32 v[28:29], v[200:201], v[46:47], v[30:31] op_sel_hi:[0,1,1]
	v_pk_fma_f32 v[30:31], v[200:201], v[44:45], v[36:37] op_sel:[1,0,0]
	v_pk_add_f32 v[28:29], v[28:29], v[30:31]
	s_nop 1
	v_add_f32_dpp v28, v28, v28 quad_perm:[1,0,3,2] row_mask:0xf bank_mask:0xf bound_ctrl:1
	v_add_f32_dpp v29, v29, v29 quad_perm:[1,0,3,2] row_mask:0xf bank_mask:0xf bound_ctrl:1
	s_nop 0
	v_add_f32_dpp v28, v28, v28 quad_perm:[2,3,0,1] row_mask:0xf bank_mask:0xf bound_ctrl:1
	v_add_f32_dpp v29, v29, v29 quad_perm:[2,3,0,1] row_mask:0xf bank_mask:0xf bound_ctrl:1
	s_nop 0
	v_mov_b32_dpp v30, v28 row_half_mirror row_mask:0xf bank_mask:0xf bound_ctrl:1
	v_mov_b32_dpp v31, v29 row_half_mirror row_mask:0xf bank_mask:0xf bound_ctrl:1
	s_and_saveexec_b64 s[20:21], s[14:15]
	v_pk_add_f32 v[28:29], v[28:29], v[30:31]
	ds_write_b64 v153, v[28:29] offset:49408
	s_or_b64 exec, exec, s[20:21]
	s_waitcnt lgkmcnt(1)
	v_pk_mul_f32 v[202:203], v[42:43], v[66:67] op_sel_hi:[0,1]
	v_pk_fma_f32 v[202:203], v[40:41], v[2:3], v[202:203] op_sel_hi:[0,1,1]
	v_pk_mul_f32 v[42:43], v[42:43], v[64:65] op_sel:[1,0]
	v_pk_fma_f32 v[40:41], v[40:41], v[68:69], v[42:43] op_sel:[1,0,0]
	s_waitcnt lgkmcnt(0)
	v_pk_fma_f32 v[42:43], v[32:33], v[62:63], v[202:203] op_sel_hi:[0,1,1]
	v_pk_fma_f32 v[32:33], v[32:33], v[60:61], v[40:41] op_sel:[1,0,0]
	v_pk_fma_f32 v[40:41], v[34:35], v[46:47], v[42:43] op_sel_hi:[0,1,1]
	v_pk_fma_f32 v[32:33], v[34:35], v[44:45], v[32:33] op_sel:[1,0,0]
	v_pk_add_f32 v[32:33], v[40:41], v[32:33]
	ds_read_b128 v[70:73], v152 offset:4608
	ds_read_b128 v[154:157], v152 offset:4624
	ds_read_b128 v[158:161], v152 offset:8704
	ds_read_b128 v[166:169], v152 offset:8720
	ds_read_b128 v[170:173], v152 offset:12800
	ds_read_b128 v[174:177], v152 offset:12816
	ds_read_b128 v[178:181], v152 offset:16896
	ds_read_b128 v[198:201], v152 offset:16912
	ds_read_b64 v[74:75], v151 offset:20992
	ds_read_b128 v[36:39], v1 offset:768
	ds_read_b128 v[28:31], v1 offset:784
	v_add_f32_dpp v32, v32, v32 quad_perm:[1,0,3,2] row_mask:0xf bank_mask:0xf bound_ctrl:1
	v_add_f32_dpp v33, v33, v33 quad_perm:[1,0,3,2] row_mask:0xf bank_mask:0xf bound_ctrl:1
	s_nop 0
	v_add_f32_dpp v32, v32, v32 quad_perm:[2,3,0,1] row_mask:0xf bank_mask:0xf bound_ctrl:1
	v_add_f32_dpp v33, v33, v33 quad_perm:[2,3,0,1] row_mask:0xf bank_mask:0xf bound_ctrl:1
	s_nop 0
	v_add_f32_dpp v32, v32, v32 row_half_mirror row_mask:0xf bank_mask:0xf bound_ctrl:1
	v_add_f32_dpp v33, v33, v33 row_half_mirror row_mask:0xf bank_mask:0xf bound_ctrl:1
	s_waitcnt lgkmcnt(8)
	v_pk_mul_f32 v[34:35], v[158:159], v[32:33] op_sel_hi:[0,1]
	s_waitcnt lgkmcnt(2)
	v_pk_fma_f32 v[34:35], v[170:171], v[74:75], v[34:35] op_sel_hi:[0,1,1] neg_lo:[0,0,1] neg_hi:[0,0,1]
	v_pk_fma_f32 v[2:3], v[2:3], v[70:71], v[34:35] op_sel_hi:[1,0,1]
	v_pk_mul_f32 v[34:35], v[158:159], v[32:33] op_sel:[1,0]
	v_pk_mul_f32 v[42:43], v[160:161], v[32:33] op_sel_hi:[0,1]
	v_pk_fma_f32 v[34:35], v[170:171], v[74:75], v[34:35] op_sel:[1,0,0] neg_lo:[0,0,1] neg_hi:[0,0,1]
	v_pk_fma_f32 v[42:43], v[172:173], v[74:75], v[42:43] op_sel_hi:[0,1,1] neg_lo:[0,0,1] neg_hi:[0,0,1]
	v_pk_fma_f32 v[68:69], v[68:69], v[70:71], v[34:35] op_sel:[0,1,0]
	v_pk_fma_f32 v[66:67], v[66:67], v[72:73], v[42:43] op_sel_hi:[1,0,1]
	v_pk_mul_f32 v[70:71], v[160:161], v[32:33] op_sel:[1,0]
	v_pk_fma_f32 v[70:71], v[172:173], v[74:75], v[70:71] op_sel:[1,0,0] neg_lo:[0,0,1] neg_hi:[0,0,1]
	v_pk_fma_f32 v[40:41], v[178:179], v[68:69], 0 op_sel:[1,0,0] op_sel_hi:[1,1,0]
	v_pk_fma_f32 v[64:65], v[64:65], v[72:73], v[70:71] op_sel:[0,1,0]
	v_pk_fma_f32 v[40:41], v[180:181], v[64:65], v[40:41] op_sel:[1,0,0]
	v_pk_mul_f32 v[42:43], v[166:167], v[32:33] op_sel_hi:[0,1]
	v_pk_fma_f32 v[42:43], v[174:175], v[74:75], v[42:43] op_sel_hi:[0,1,1] neg_lo:[0,0,1] neg_hi:[0,0,1]
	v_pk_fma_f32 v[62:63], v[62:63], v[154:155], v[42:43] op_sel_hi:[1,0,1]
	v_pk_mul_f32 v[42:43], v[166:167], v[32:33] op_sel:[1,0]
	v_pk_fma_f32 v[34:35], v[178:179], v[2:3], 0 op_sel_hi:[0,1,0]
	v_pk_fma_f32 v[42:43], v[174:175], v[74:75], v[42:43] op_sel:[1,0,0] neg_lo:[0,0,1] neg_hi:[0,0,1]
	v_pk_fma_f32 v[60:61], v[60:61], v[154:155], v[42:43] op_sel:[0,1,0]
	v_pk_mul_f32 v[42:43], v[168:169], v[32:33] op_sel_hi:[0,1]
	v_pk_fma_f32 v[34:35], v[180:181], v[66:67], v[34:35] op_sel_hi:[0,1,1]
	v_pk_fma_f32 v[42:43], v[176:177], v[74:75], v[42:43] op_sel_hi:[0,1,1] neg_lo:[0,0,1] neg_hi:[0,0,1]
	v_pk_mul_f32 v[32:33], v[168:169], v[32:33] op_sel:[1,0]
	v_pk_fma_f32 v[34:35], v[198:199], v[62:63], v[34:35] op_sel_hi:[0,1,1]
	v_pk_fma_f32 v[46:47], v[46:47], v[156:157], v[42:43] op_sel_hi:[1,0,1]
	v_pk_fma_f32 v[32:33], v[176:177], v[74:75], v[32:33] op_sel:[1,0,0] neg_lo:[0,0,1] neg_hi:[0,0,1]
	v_pk_fma_f32 v[40:41], v[198:199], v[60:61], v[40:41] op_sel:[1,0,0]
	v_pk_fma_f32 v[44:45], v[44:45], v[156:157], v[32:33] op_sel:[0,1,0]
	v_pk_fma_f32 v[32:33], v[200:201], v[46:47], v[34:35] op_sel_hi:[0,1,1]
	v_pk_fma_f32 v[34:35], v[200:201], v[44:45], v[40:41] op_sel:[1,0,0]
	v_pk_add_f32 v[32:33], v[32:33], v[34:35]
	s_nop 1
	v_add_f32_dpp v32, v32, v32 quad_perm:[1,0,3,2] row_mask:0xf bank_mask:0xf bound_ctrl:1
	v_add_f32_dpp v33, v33, v33 quad_perm:[1,0,3,2] row_mask:0xf bank_mask:0xf bound_ctrl:1
	s_nop 0
	v_add_f32_dpp v32, v32, v32 quad_perm:[2,3,0,1] row_mask:0xf bank_mask:0xf bound_ctrl:1
	v_add_f32_dpp v33, v33, v33 quad_perm:[2,3,0,1] row_mask:0xf bank_mask:0xf bound_ctrl:1
	s_nop 0
	v_mov_b32_dpp v34, v32 row_half_mirror row_mask:0xf bank_mask:0xf bound_ctrl:1
	v_mov_b32_dpp v35, v33 row_half_mirror row_mask:0xf bank_mask:0xf bound_ctrl:1
	s_and_saveexec_b64 s[20:21], s[14:15]
	v_pk_add_f32 v[32:33], v[32:33], v[34:35]
	ds_write_b64 v153, v[32:33] offset:49664
	s_or_b64 exec, exec, s[20:21]
	s_waitcnt lgkmcnt(1)
	v_pk_mul_f32 v[202:203], v[38:39], v[66:67] op_sel_hi:[0,1]
	v_pk_fma_f32 v[202:203], v[36:37], v[2:3], v[202:203] op_sel_hi:[0,1,1]
	v_pk_mul_f32 v[38:39], v[38:39], v[64:65] op_sel:[1,0]
	v_pk_fma_f32 v[36:37], v[36:37], v[68:69], v[38:39] op_sel:[1,0,0]
	s_waitcnt lgkmcnt(0)
	v_pk_fma_f32 v[38:39], v[28:29], v[62:63], v[202:203] op_sel_hi:[0,1,1]
	v_pk_fma_f32 v[28:29], v[28:29], v[60:61], v[36:37] op_sel:[1,0,0]
	v_pk_fma_f32 v[36:37], v[30:31], v[46:47], v[38:39] op_sel_hi:[0,1,1]
	v_pk_fma_f32 v[28:29], v[30:31], v[44:45], v[28:29] op_sel:[1,0,0]
	v_pk_add_f32 v[28:29], v[36:37], v[28:29]
	ds_read_b128 v[70:73], v152 offset:4864
	ds_read_b128 v[154:157], v152 offset:4880
	ds_read_b128 v[158:161], v152 offset:8960
	ds_read_b128 v[166:169], v152 offset:8976
	ds_read_b128 v[170:173], v152 offset:13056
	ds_read_b128 v[174:177], v152 offset:13072
	ds_read_b128 v[178:181], v152 offset:17152
	ds_read_b128 v[198:201], v152 offset:17168
	ds_read_b64 v[74:75], v151 offset:21248
	ds_read_b128 v[40:43], v1 offset:1024
	ds_read_b128 v[32:35], v1 offset:1040
	v_add_f32_dpp v28, v28, v28 quad_perm:[1,0,3,2] row_mask:0xf bank_mask:0xf bound_ctrl:1
	v_add_f32_dpp v29, v29, v29 quad_perm:[1,0,3,2] row_mask:0xf bank_mask:0xf bound_ctrl:1
	s_nop 0
	v_add_f32_dpp v28, v28, v28 quad_perm:[2,3,0,1] row_mask:0xf bank_mask:0xf bound_ctrl:1
	v_add_f32_dpp v29, v29, v29 quad_perm:[2,3,0,1] row_mask:0xf bank_mask:0xf bound_ctrl:1
	s_nop 0
	v_add_f32_dpp v36, v28, v28 row_half_mirror row_mask:0xf bank_mask:0xf bound_ctrl:1
	v_add_f32_dpp v37, v29, v29 row_half_mirror row_mask:0xf bank_mask:0xf bound_ctrl:1
	s_waitcnt lgkmcnt(8)
	v_pk_mul_f32 v[28:29], v[158:159], v[36:37] op_sel_hi:[0,1]
	s_waitcnt lgkmcnt(2)
	v_pk_fma_f32 v[28:29], v[170:171], v[74:75], v[28:29] op_sel_hi:[0,1,1] neg_lo:[0,0,1] neg_hi:[0,0,1]
	v_pk_fma_f32 v[2:3], v[2:3], v[70:71], v[28:29] op_sel_hi:[1,0,1]
	v_pk_mul_f32 v[28:29], v[158:159], v[36:37] op_sel:[1,0]
	v_pk_mul_f32 v[30:31], v[160:161], v[36:37] op_sel_hi:[0,1]
	v_pk_fma_f32 v[28:29], v[170:171], v[74:75], v[28:29] op_sel:[1,0,0] neg_lo:[0,0,1] neg_hi:[0,0,1]
	v_pk_fma_f32 v[30:31], v[172:173], v[74:75], v[30:31] op_sel_hi:[0,1,1] neg_lo:[0,0,1] neg_hi:[0,0,1]
	v_pk_fma_f32 v[28:29], v[68:69], v[70:71], v[28:29] op_sel:[0,1,0]
	v_pk_fma_f32 v[30:31], v[66:67], v[72:73], v[30:31] op_sel_hi:[1,0,1]
	v_pk_mul_f32 v[70:71], v[160:161], v[36:37] op_sel:[1,0]
	v_pk_fma_f32 v[70:71], v[172:173], v[74:75], v[70:71] op_sel:[1,0,0] neg_lo:[0,0,1] neg_hi:[0,0,1]
	v_pk_fma_f32 v[68:69], v[178:179], v[28:29], 0 op_sel:[1,0,0] op_sel_hi:[1,1,0]
	v_pk_fma_f32 v[64:65], v[64:65], v[72:73], v[70:71] op_sel:[0,1,0]
	v_pk_fma_f32 v[66:67], v[180:181], v[64:65], v[68:69] op_sel:[1,0,0]
	v_pk_mul_f32 v[68:69], v[166:167], v[36:37] op_sel_hi:[0,1]
	v_pk_fma_f32 v[68:69], v[174:175], v[74:75], v[68:69] op_sel_hi:[0,1,1] neg_lo:[0,0,1] neg_hi:[0,0,1]
	v_pk_fma_f32 v[62:63], v[62:63], v[154:155], v[68:69] op_sel_hi:[1,0,1]
	v_pk_mul_f32 v[68:69], v[166:167], v[36:37] op_sel:[1,0]
	v_pk_fma_f32 v[38:39], v[178:179], v[2:3], 0 op_sel_hi:[0,1,0]
	v_pk_fma_f32 v[68:69], v[174:175], v[74:75], v[68:69] op_sel:[1,0,0] neg_lo:[0,0,1] neg_hi:[0,0,1]
	v_pk_fma_f32 v[38:39], v[180:181], v[30:31], v[38:39] op_sel_hi:[0,1,1]
	v_pk_fma_f32 v[60:61], v[60:61], v[154:155], v[68:69] op_sel:[0,1,0]
	v_pk_fma_f32 v[70:71], v[198:199], v[60:61], v[66:67] op_sel:[1,0,0]
	v_pk_mul_f32 v[66:67], v[168:169], v[36:37] op_sel_hi:[0,1]
	v_pk_fma_f32 v[66:67], v[176:177], v[74:75], v[66:67] op_sel_hi:[0,1,1] neg_lo:[0,0,1] neg_hi:[0,0,1]
	v_pk_mul_f32 v[36:37], v[168:169], v[36:37] op_sel:[1,0]
	v_pk_fma_f32 v[38:39], v[198:199], v[62:63], v[38:39] op_sel_hi:[0,1,1]
	v_pk_fma_f32 v[66:67], v[46:47], v[156:157], v[66:67] op_sel_hi:[1,0,1]
	v_pk_fma_f32 v[36:37], v[176:177], v[74:75], v[36:37] op_sel:[1,0,0] neg_lo:[0,0,1] neg_hi:[0,0,1]
	v_pk_fma_f32 v[68:69], v[44:45], v[156:157], v[36:37] op_sel:[0,1,0]
	v_pk_fma_f32 v[36:37], v[200:201], v[66:67], v[38:39] op_sel_hi:[0,1,1]
	v_pk_fma_f32 v[38:39], v[200:201], v[68:69], v[70:71] op_sel:[1,0,0]
	v_pk_add_f32 v[36:37], v[36:37], v[38:39]
	s_nop 1
	v_add_f32_dpp v36, v36, v36 quad_perm:[1,0,3,2] row_mask:0xf bank_mask:0xf bound_ctrl:1
	v_add_f32_dpp v37, v37, v37 quad_perm:[1,0,3,2] row_mask:0xf bank_mask:0xf bound_ctrl:1
	s_nop 0
	v_add_f32_dpp v36, v36, v36 quad_perm:[2,3,0,1] row_mask:0xf bank_mask:0xf bound_ctrl:1
	v_add_f32_dpp v37, v37, v37 quad_perm:[2,3,0,1] row_mask:0xf bank_mask:0xf bound_ctrl:1
	s_nop 0
	v_mov_b32_dpp v38, v36 row_half_mirror row_mask:0xf bank_mask:0xf bound_ctrl:1
	v_mov_b32_dpp v39, v37 row_half_mirror row_mask:0xf bank_mask:0xf bound_ctrl:1
	s_and_saveexec_b64 s[20:21], s[14:15]
	v_pk_add_f32 v[36:37], v[36:37], v[38:39]
	ds_write_b64 v153, v[36:37] offset:49920
	s_or_b64 exec, exec, s[20:21]
	s_waitcnt lgkmcnt(1)
	v_pk_mul_f32 v[202:203], v[42:43], v[30:31] op_sel_hi:[0,1]
	v_pk_fma_f32 v[202:203], v[40:41], v[2:3], v[202:203] op_sel_hi:[0,1,1]
	v_pk_mul_f32 v[42:43], v[42:43], v[64:65] op_sel:[1,0]
	v_pk_fma_f32 v[40:41], v[40:41], v[28:29], v[42:43] op_sel:[1,0,0]
	s_waitcnt lgkmcnt(0)
	v_pk_fma_f32 v[42:43], v[32:33], v[62:63], v[202:203] op_sel_hi:[0,1,1]
	v_pk_fma_f32 v[32:33], v[32:33], v[60:61], v[40:41] op_sel:[1,0,0]
	v_pk_fma_f32 v[40:41], v[34:35], v[66:67], v[42:43] op_sel_hi:[0,1,1]
	v_pk_fma_f32 v[32:33], v[34:35], v[68:69], v[32:33] op_sel:[1,0,0]
	v_pk_add_f32 v[32:33], v[40:41], v[32:33]
	ds_read_b128 v[70:73], v152 offset:5120
	ds_read_b128 v[154:157], v152 offset:5136
	ds_read_b128 v[158:161], v152 offset:9216
	ds_read_b128 v[166:169], v152 offset:9232
	ds_read_b128 v[170:173], v152 offset:13312
	ds_read_b128 v[174:177], v152 offset:13328
	ds_read_b128 v[178:181], v152 offset:17408
	ds_read_b128 v[198:201], v152 offset:17424
	ds_read_b64 v[74:75], v151 offset:21504
	ds_read_b128 v[44:47], v1 offset:1280
	ds_read_b128 v[36:39], v1 offset:1296
	v_add_f32_dpp v32, v32, v32 quad_perm:[1,0,3,2] row_mask:0xf bank_mask:0xf bound_ctrl:1
	v_add_f32_dpp v33, v33, v33 quad_perm:[1,0,3,2] row_mask:0xf bank_mask:0xf bound_ctrl:1
	s_nop 0
	v_add_f32_dpp v32, v32, v32 quad_perm:[2,3,0,1] row_mask:0xf bank_mask:0xf bound_ctrl:1
	v_add_f32_dpp v33, v33, v33 quad_perm:[2,3,0,1] row_mask:0xf bank_mask:0xf bound_ctrl:1
	s_nop 0
	v_add_f32_dpp v32, v32, v32 row_half_mirror row_mask:0xf bank_mask:0xf bound_ctrl:1
	v_add_f32_dpp v33, v33, v33 row_half_mirror row_mask:0xf bank_mask:0xf bound_ctrl:1
	s_waitcnt lgkmcnt(8)
	v_pk_mul_f32 v[34:35], v[158:159], v[32:33] op_sel_hi:[0,1]
	s_waitcnt lgkmcnt(2)
	v_pk_fma_f32 v[34:35], v[170:171], v[74:75], v[34:35] op_sel_hi:[0,1,1] neg_lo:[0,0,1] neg_hi:[0,0,1]
	v_pk_fma_f32 v[2:3], v[2:3], v[70:71], v[34:35] op_sel_hi:[1,0,1]
	v_pk_mul_f32 v[34:35], v[158:159], v[32:33] op_sel:[1,0]
	v_pk_mul_f32 v[42:43], v[160:161], v[32:33] op_sel_hi:[0,1]
	v_pk_fma_f32 v[34:35], v[170:171], v[74:75], v[34:35] op_sel:[1,0,0] neg_lo:[0,0,1] neg_hi:[0,0,1]
	v_pk_fma_f32 v[42:43], v[172:173], v[74:75], v[42:43] op_sel_hi:[0,1,1] neg_lo:[0,0,1] neg_hi:[0,0,1]
	v_pk_fma_f32 v[40:41], v[28:29], v[70:71], v[34:35] op_sel:[0,1,0]
	v_pk_fma_f32 v[42:43], v[30:31], v[72:73], v[42:43] op_sel_hi:[1,0,1]
	v_pk_mul_f32 v[70:71], v[160:161], v[32:33] op_sel:[1,0]
	v_pk_fma_f32 v[70:71], v[172:173], v[74:75], v[70:71] op_sel:[1,0,0] neg_lo:[0,0,1] neg_hi:[0,0,1]
	v_pk_fma_f32 v[34:35], v[178:179], v[40:41], 0 op_sel:[1,0,0] op_sel_hi:[1,1,0]
	v_pk_fma_f32 v[64:65], v[64:65], v[72:73], v[70:71] op_sel:[0,1,0]
	v_pk_fma_f32 v[30:31], v[180:181], v[64:65], v[34:35] op_sel:[1,0,0]
	v_pk_mul_f32 v[34:35], v[166:167], v[32:33] op_sel_hi:[0,1]
	v_pk_fma_f32 v[34:35], v[174:175], v[74:75], v[34:35] op_sel_hi:[0,1,1] neg_lo:[0,0,1] neg_hi:[0,0,1]
	v_pk_fma_f32 v[62:63], v[62:63], v[154:155], v[34:35] op_sel_hi:[1,0,1]
	v_pk_mul_f32 v[34:35], v[166:167], v[32:33] op_sel:[1,0]
	v_pk_fma_f32 v[28:29], v[178:179], v[2:3], 0 op_sel_hi:[0,1,0]
	v_pk_fma_f32 v[34:35], v[174:175], v[74:75], v[34:35] op_sel:[1,0,0] neg_lo:[0,0,1] neg_hi:[0,0,1]
	v_pk_fma_f32 v[60:61], v[60:61], v[154:155], v[34:35] op_sel:[0,1,0]
	v_pk_mul_f32 v[34:35], v[168:169], v[32:33] op_sel_hi:[0,1]
	v_pk_fma_f32 v[34:35], v[176:177], v[74:75], v[34:35] op_sel_hi:[0,1,1] neg_lo:[0,0,1] neg_hi:[0,0,1]
	v_pk_fma_f32 v[72:73], v[66:67], v[156:157], v[34:35] op_sel_hi:[1,0,1]
	v_pk_mul_f32 v[32:33], v[168:169], v[32:33] op_sel:[1,0]
	v_pk_fma_f32 v[28:29], v[180:181], v[42:43], v[28:29] op_sel_hi:[0,1,1]
	v_pk_fma_f32 v[32:33], v[176:177], v[74:75], v[32:33] op_sel:[1,0,0] neg_lo:[0,0,1] neg_hi:[0,0,1]
	v_pk_fma_f32 v[28:29], v[198:199], v[62:63], v[28:29] op_sel_hi:[0,1,1]
	v_pk_fma_f32 v[30:31], v[198:199], v[60:61], v[30:31] op_sel:[1,0,0]
	v_pk_fma_f32 v[74:75], v[68:69], v[156:157], v[32:33] op_sel:[0,1,0]
	v_pk_fma_f32 v[28:29], v[200:201], v[72:73], v[28:29] op_sel_hi:[0,1,1]
	v_pk_fma_f32 v[30:31], v[200:201], v[74:75], v[30:31] op_sel:[1,0,0]
	v_pk_add_f32 v[28:29], v[28:29], v[30:31]
	s_nop 1
	v_add_f32_dpp v28, v28, v28 quad_perm:[1,0,3,2] row_mask:0xf bank_mask:0xf bound_ctrl:1
	v_add_f32_dpp v29, v29, v29 quad_perm:[1,0,3,2] row_mask:0xf bank_mask:0xf bound_ctrl:1
	s_nop 0
	v_add_f32_dpp v28, v28, v28 quad_perm:[2,3,0,1] row_mask:0xf bank_mask:0xf bound_ctrl:1
	v_add_f32_dpp v29, v29, v29 quad_perm:[2,3,0,1] row_mask:0xf bank_mask:0xf bound_ctrl:1
	s_nop 0
	v_mov_b32_dpp v30, v28 row_half_mirror row_mask:0xf bank_mask:0xf bound_ctrl:1
	v_mov_b32_dpp v31, v29 row_half_mirror row_mask:0xf bank_mask:0xf bound_ctrl:1
	s_and_saveexec_b64 s[20:21], s[14:15]
	v_pk_add_f32 v[28:29], v[28:29], v[30:31]
	ds_write_b64 v153, v[28:29] offset:50176
	s_or_b64 exec, exec, s[20:21]
	s_waitcnt lgkmcnt(1)
	v_pk_mul_f32 v[66:67], v[46:47], v[42:43] op_sel_hi:[0,1]
	v_pk_fma_f32 v[66:67], v[44:45], v[2:3], v[66:67] op_sel_hi:[0,1,1]
	v_pk_mul_f32 v[46:47], v[46:47], v[64:65] op_sel:[1,0]
	v_pk_fma_f32 v[44:45], v[44:45], v[40:41], v[46:47] op_sel:[1,0,0]
	s_waitcnt lgkmcnt(0)
	v_pk_fma_f32 v[46:47], v[36:37], v[62:63], v[66:67] op_sel_hi:[0,1,1]
	v_pk_fma_f32 v[36:37], v[36:37], v[60:61], v[44:45] op_sel:[1,0,0]
	v_pk_fma_f32 v[44:45], v[38:39], v[72:73], v[46:47] op_sel_hi:[0,1,1]
	v_pk_fma_f32 v[36:37], v[38:39], v[74:75], v[36:37] op_sel:[1,0,0]
	v_pk_add_f32 v[36:37], v[44:45], v[36:37]
	ds_read_b128 v[154:157], v152 offset:5376
	ds_read_b128 v[158:161], v152 offset:5392
	ds_read_b128 v[166:169], v152 offset:9472
	ds_read_b128 v[170:173], v152 offset:9488
	ds_read_b128 v[174:177], v152 offset:13568
	ds_read_b128 v[178:181], v152 offset:13584
	ds_read_b128 v[198:201], v152 offset:17664
	ds_read_b128 v[202:205], v152 offset:17680
	ds_read_b64 v[206:207], v151 offset:21760
	ds_read_b128 v[32:35], v1 offset:1536
	ds_read_b128 v[28:31], v1 offset:1552
	v_add_f32_dpp v36, v36, v36 quad_perm:[1,0,3,2] row_mask:0xf bank_mask:0xf bound_ctrl:1
	v_add_f32_dpp v37, v37, v37 quad_perm:[1,0,3,2] row_mask:0xf bank_mask:0xf bound_ctrl:1
	s_nop 0
	s_waitcnt lgkmcnt(6)
	v_add_f32_dpp v36, v36, v36 quad_perm:[2,3,0,1] row_mask:0xf bank_mask:0xf bound_ctrl:1
	v_add_f32_dpp v37, v37, v37 quad_perm:[2,3,0,1] row_mask:0xf bank_mask:0xf bound_ctrl:1
	s_nop 0
	v_add_f32_dpp v36, v36, v36 row_half_mirror row_mask:0xf bank_mask:0xf bound_ctrl:1
	v_add_f32_dpp v37, v37, v37 row_half_mirror row_mask:0xf bank_mask:0xf bound_ctrl:1
	s_nop 0
	v_pk_mul_f32 v[38:39], v[166:167], v[36:37] op_sel_hi:[0,1]
	s_waitcnt lgkmcnt(2)
	v_pk_fma_f32 v[38:39], v[174:175], v[206:207], v[38:39] op_sel_hi:[0,1,1] neg_lo:[0,0,1] neg_hi:[0,0,1]
	v_pk_fma_f32 v[70:71], v[2:3], v[154:155], v[38:39] op_sel_hi:[1,0,1]
	v_pk_mul_f32 v[2:3], v[166:167], v[36:37] op_sel:[1,0]
	s_nop 0
	v_pk_fma_f32 v[2:3], v[174:175], v[206:207], v[2:3] op_sel:[1,0,0] neg_lo:[0,0,1] neg_hi:[0,0,1]
	s_nop 0
	v_pk_fma_f32 v[68:69], v[40:41], v[154:155], v[2:3] op_sel:[0,1,0]
	v_pk_mul_f32 v[40:41], v[168:169], v[36:37] op_sel_hi:[0,1]
	v_pk_fma_f32 v[40:41], v[176:177], v[206:207], v[40:41] op_sel_hi:[0,1,1] neg_lo:[0,0,1] neg_hi:[0,0,1]
	v_pk_fma_f32 v[66:67], v[42:43], v[156:157], v[40:41] op_sel_hi:[1,0,1]
	v_pk_mul_f32 v[42:43], v[168:169], v[36:37] op_sel:[1,0]
	v_pk_fma_f32 v[42:43], v[176:177], v[206:207], v[42:43] op_sel:[1,0,0] neg_lo:[0,0,1] neg_hi:[0,0,1]
	v_pk_fma_f32 v[38:39], v[198:199], v[68:69], 0 op_sel:[1,0,0] op_sel_hi:[1,1,0]
	v_pk_fma_f32 v[64:65], v[64:65], v[156:157], v[42:43] op_sel:[0,1,0]
	v_pk_fma_f32 v[38:39], v[200:201], v[64:65], v[38:39] op_sel:[1,0,0]
	v_pk_mul_f32 v[40:41], v[170:171], v[36:37] op_sel_hi:[0,1]
	v_pk_fma_f32 v[40:41], v[178:179], v[206:207], v[40:41] op_sel_hi:[0,1,1] neg_lo:[0,0,1] neg_hi:[0,0,1]
	v_pk_fma_f32 v[62:63], v[62:63], v[158:159], v[40:41] op_sel_hi:[1,0,1]
	v_pk_mul_f32 v[40:41], v[170:171], v[36:37] op_sel:[1,0]
	v_mov_b32_e32 v42, v173
	v_pk_fma_f32 v[40:41], v[178:179], v[206:207], v[40:41] op_sel:[1,0,0] neg_lo:[0,0,1] neg_hi:[0,0,1]
	v_pk_fma_f32 v[2:3], v[198:199], v[70:71], 0 op_sel_hi:[0,1,0]
	v_pk_fma_f32 v[60:61], v[60:61], v[158:159], v[40:41] op_sel:[0,1,0]
	v_pk_mul_f32 v[40:41], v[172:173], v[36:37] op_sel_hi:[0,1]
	v_pk_fma_f32 v[40:41], v[180:181], v[206:207], v[40:41] op_sel_hi:[0,1,1] neg_lo:[0,0,1] neg_hi:[0,0,1]
	v_pk_mul_f32 v[36:37], v[42:43], v[36:37] op_sel_hi:[0,1]
	v_pk_fma_f32 v[2:3], v[200:201], v[66:67], v[2:3] op_sel_hi:[0,1,1]
	v_pk_fma_f32 v[46:47], v[72:73], v[160:161], v[40:41] op_sel_hi:[1,0,1]
	v_mov_b32_e32 v40, v161
	v_pk_fma_f32 v[36:37], v[180:181], v[206:207], v[36:37] op_sel:[1,0,0] neg_lo:[0,0,1] neg_hi:[0,0,1]
	v_pk_fma_f32 v[2:3], v[202:203], v[62:63], v[2:3] op_sel_hi:[0,1,1]
	v_pk_fma_f32 v[38:39], v[202:203], v[60:61], v[38:39] op_sel:[1,0,0]
	v_pk_fma_f32 v[44:45], v[74:75], v[40:41], v[36:37] op_sel_hi:[1,0,1]
	v_pk_fma_f32 v[2:3], v[204:205], v[46:47], v[2:3] op_sel_hi:[0,1,1]
	v_pk_fma_f32 v[36:37], v[204:205], v[44:45], v[38:39] op_sel:[1,0,0]
	v_pk_add_f32 v[2:3], v[2:3], v[36:37]
	s_nop 1
	v_add_f32_dpp v2, v2, v2 quad_perm:[1,0,3,2] row_mask:0xf bank_mask:0xf bound_ctrl:1
	v_add_f32_dpp v3, v3, v3 quad_perm:[1,0,3,2] row_mask:0xf bank_mask:0xf bound_ctrl:1
	s_nop 0
	v_add_f32_dpp v2, v2, v2 quad_perm:[2,3,0,1] row_mask:0xf bank_mask:0xf bound_ctrl:1
	v_add_f32_dpp v3, v3, v3 quad_perm:[2,3,0,1] row_mask:0xf bank_mask:0xf bound_ctrl:1
	s_nop 0
	v_mov_b32_dpp v36, v2 row_half_mirror row_mask:0xf bank_mask:0xf bound_ctrl:1
	v_mov_b32_dpp v37, v3 row_half_mirror row_mask:0xf bank_mask:0xf bound_ctrl:1
	s_and_saveexec_b64 s[20:21], s[14:15]
	v_pk_add_f32 v[2:3], v[2:3], v[36:37]
	ds_write_b64 v153, v[2:3] offset:50432
	s_or_b64 exec, exec, s[20:21]

.LBB0_612:
	s_andn2_saveexec_b64 s[0:1], s[0:1]
	s_cbranch_execz .LBB0_624
	v_pk_mul_f32 v[2:3], v[66:67], v[34:35] op_sel_hi:[1,0]
	v_pk_fma_f32 v[2:3], v[70:71], v[32:33], v[2:3] op_sel_hi:[1,0,1]
	v_pk_mul_f32 v[34:35], v[64:65], v[34:35] op_sel:[0,1]
	v_pk_fma_f32 v[2:3], v[62:63], v[28:29], v[2:3] op_sel_hi:[1,0,1]
	v_pk_fma_f32 v[32:33], v[68:69], v[32:33], v[34:35] op_sel:[0,1,0]
	v_pk_fma_f32 v[2:3], v[46:47], v[30:31], v[2:3] op_sel_hi:[1,0,1]
	v_pk_fma_f32 v[28:29], v[60:61], v[28:29], v[32:33] op_sel:[0,1,0]
	v_pk_fma_f32 v[28:29], v[44:45], v[30:31], v[28:29] op_sel:[0,1,0]
	s_and_b32 s20, s25, 1
	v_pk_add_f32 v[2:3], v[2:3], v[28:29]
	s_mul_i32 s21, s20, 0x6000
	s_add_i32 s21, s21, 0
	v_add_f32_dpp v2, v2, v2 quad_perm:[1,0,3,2] row_mask:0xf bank_mask:0xf bound_ctrl:1
	v_add_f32_dpp v3, v3, v3 quad_perm:[1,0,3,2] row_mask:0xf bank_mask:0xf bound_ctrl:1
	s_bitcmp1_b32 s25, 0
	v_lshl_add_u32 v152, v97, 2, s21
	v_mov_b32_dpp v28, v2 quad_perm:[2,3,0,1] row_mask:0xf bank_mask:0xf bound_ctrl:1
	v_mov_b32_dpp v29, v3 quad_perm:[2,3,0,1] row_mask:0xf bank_mask:0xf bound_ctrl:1
	v_lshl_add_u32 v1, v98, 2, s21
	s_cselect_b32 s21, 0x6000, 0
	v_pk_add_f32 v[2:3], v[2:3], v[28:29]
	v_add_u32_e32 v151, s21, v143
	ds_read_b128 v[72:75], v152 offset:5632
	ds_read_b128 v[154:157], v152 offset:5648
	ds_read_b128 v[158:161], v152 offset:9728
	ds_read_b128 v[166:169], v152 offset:9744
	ds_read_b128 v[170:173], v152 offset:13824
	ds_read_b128 v[174:177], v152 offset:13840
	ds_read_b128 v[178:181], v152 offset:17920
	ds_read_b128 v[198:201], v152 offset:17936
	ds_read_b64 v[202:203], v1 offset:22016
	ds_read_b128 v[40:43], v151 offset:1792
	ds_read_b128 v[36:39], v151 offset:1808
	v_add_f32_dpp v28, v2, v2 row_half_mirror row_mask:0xf bank_mask:0xf bound_ctrl:1
	v_add_f32_dpp v29, v3, v3 row_half_mirror row_mask:0xf bank_mask:0xf bound_ctrl:1
	s_lshl_b32 s20, s20, 12
	s_waitcnt lgkmcnt(8)
	v_pk_mul_f32 v[2:3], v[158:159], v[28:29] op_sel_hi:[0,1]
	s_waitcnt lgkmcnt(2)
	v_pk_fma_f32 v[2:3], v[170:171], v[202:203], v[2:3] op_sel_hi:[0,1,1] neg_lo:[0,0,1] neg_hi:[0,0,1]
	v_pk_mul_f32 v[30:31], v[158:159], v[28:29] op_sel:[1,0]
	v_pk_fma_f32 v[2:3], v[70:71], v[72:73], v[2:3] op_sel_hi:[1,0,1]
	v_pk_fma_f32 v[30:31], v[170:171], v[202:203], v[30:31] op_sel:[1,0,0] neg_lo:[0,0,1] neg_hi:[0,0,1]
	v_pk_mul_f32 v[34:35], v[160:161], v[28:29] op_sel_hi:[0,1]
	v_pk_fma_f32 v[32:33], v[68:69], v[72:73], v[30:31] op_sel:[0,1,0]
	v_pk_fma_f32 v[34:35], v[172:173], v[202:203], v[34:35] op_sel_hi:[0,1,1] neg_lo:[0,0,1] neg_hi:[0,0,1]
	v_pk_mul_f32 v[70:71], v[160:161], v[28:29] op_sel:[1,0]
	v_pk_fma_f32 v[34:35], v[66:67], v[74:75], v[34:35] op_sel_hi:[1,0,1]
	v_pk_fma_f32 v[70:71], v[172:173], v[202:203], v[70:71] op_sel:[1,0,0] neg_lo:[0,0,1] neg_hi:[0,0,1]
	v_pk_fma_f32 v[68:69], v[178:179], v[32:33], 0 op_sel:[1,0,0] op_sel_hi:[1,1,0]
	v_pk_fma_f32 v[64:65], v[64:65], v[74:75], v[70:71] op_sel:[0,1,0]
	v_pk_fma_f32 v[66:67], v[180:181], v[64:65], v[68:69] op_sel:[1,0,0]
	v_pk_mul_f32 v[68:69], v[166:167], v[28:29] op_sel_hi:[0,1]
	v_pk_fma_f32 v[68:69], v[174:175], v[202:203], v[68:69] op_sel_hi:[0,1,1] neg_lo:[0,0,1] neg_hi:[0,0,1]
	v_pk_fma_f32 v[62:63], v[62:63], v[154:155], v[68:69] op_sel_hi:[1,0,1]
	v_pk_mul_f32 v[68:69], v[166:167], v[28:29] op_sel:[1,0]
	v_pk_fma_f32 v[30:31], v[178:179], v[2:3], 0 op_sel_hi:[0,1,0]
	v_pk_fma_f32 v[68:69], v[174:175], v[202:203], v[68:69] op_sel:[1,0,0] neg_lo:[0,0,1] neg_hi:[0,0,1]
	v_pk_fma_f32 v[30:31], v[180:181], v[34:35], v[30:31] op_sel_hi:[0,1,1]
	v_pk_fma_f32 v[60:61], v[60:61], v[154:155], v[68:69] op_sel:[0,1,0]
	v_pk_fma_f32 v[70:71], v[198:199], v[60:61], v[66:67] op_sel:[1,0,0]
	v_pk_mul_f32 v[66:67], v[168:169], v[28:29] op_sel_hi:[0,1]
	v_pk_fma_f32 v[66:67], v[176:177], v[202:203], v[66:67] op_sel_hi:[0,1,1] neg_lo:[0,0,1] neg_hi:[0,0,1]
	v_pk_mul_f32 v[28:29], v[168:169], v[28:29] op_sel:[1,0]
	v_pk_fma_f32 v[30:31], v[198:199], v[62:63], v[30:31] op_sel_hi:[0,1,1]
	v_pk_fma_f32 v[66:67], v[46:47], v[156:157], v[66:67] op_sel_hi:[1,0,1]
	v_pk_fma_f32 v[28:29], v[176:177], v[202:203], v[28:29] op_sel:[1,0,0] neg_lo:[0,0,1] neg_hi:[0,0,1]
	v_pk_fma_f32 v[68:69], v[44:45], v[156:157], v[28:29] op_sel:[0,1,0]
	v_pk_fma_f32 v[28:29], v[200:201], v[66:67], v[30:31] op_sel_hi:[0,1,1]
	v_pk_fma_f32 v[30:31], v[200:201], v[68:69], v[70:71] op_sel:[1,0,0]
	v_pk_add_f32 v[28:29], v[28:29], v[30:31]
	v_add_u32_e32 v153, s20, v99
	s_nop 0
	v_add_f32_dpp v28, v28, v28 quad_perm:[1,0,3,2] row_mask:0xf bank_mask:0xf bound_ctrl:1
	v_add_f32_dpp v29, v29, v29 quad_perm:[1,0,3,2] row_mask:0xf bank_mask:0xf bound_ctrl:1
	s_nop 0
	v_add_f32_dpp v28, v28, v28 quad_perm:[2,3,0,1] row_mask:0xf bank_mask:0xf bound_ctrl:1
	v_add_f32_dpp v29, v29, v29 quad_perm:[2,3,0,1] row_mask:0xf bank_mask:0xf bound_ctrl:1
	s_nop 0
	v_mov_b32_dpp v30, v28 row_half_mirror row_mask:0xf bank_mask:0xf bound_ctrl:1
	v_mov_b32_dpp v31, v29 row_half_mirror row_mask:0xf bank_mask:0xf bound_ctrl:1
	s_and_saveexec_b64 s[20:21], s[14:15]
	v_pk_add_f32 v[28:29], v[28:29], v[30:31]
	ds_write_b64 v153, v[28:29] offset:50688
	s_or_b64 exec, exec, s[20:21]
	s_waitcnt lgkmcnt(1)
	v_pk_mul_f32 v[202:203], v[42:43], v[34:35] op_sel_hi:[0,1]
	v_pk_fma_f32 v[202:203], v[40:41], v[2:3], v[202:203] op_sel_hi:[0,1,1]
	v_pk_mul_f32 v[42:43], v[42:43], v[64:65] op_sel:[1,0]
	v_pk_fma_f32 v[40:41], v[40:41], v[32:33], v[42:43] op_sel:[1,0,0]
	s_waitcnt lgkmcnt(0)
	v_pk_fma_f32 v[42:43], v[36:37], v[62:63], v[202:203] op_sel_hi:[0,1,1]
	v_pk_fma_f32 v[36:37], v[36:37], v[60:61], v[40:41] op_sel:[1,0,0]
	v_pk_fma_f32 v[40:41], v[38:39], v[66:67], v[42:43] op_sel_hi:[0,1,1]
	v_pk_fma_f32 v[36:37], v[38:39], v[68:69], v[36:37] op_sel:[1,0,0]
	v_pk_add_f32 v[36:37], v[40:41], v[36:37]
	ds_read_b128 v[70:73], v152 offset:5888
	ds_read_b128 v[154:157], v152 offset:5904
	ds_read_b128 v[158:161], v152 offset:9984
	ds_read_b128 v[166:169], v152 offset:10000
	ds_read_b128 v[170:173], v152 offset:14080
	ds_read_b128 v[174:177], v152 offset:14096
	ds_read_b128 v[178:181], v152 offset:18176
	ds_read_b128 v[198:201], v152 offset:18192
	ds_read_b64 v[74:75], v1 offset:22272
	ds_read_b128 v[44:47], v151 offset:2048
	ds_read_b128 v[28:31], v151 offset:2064
	v_add_f32_dpp v36, v36, v36 quad_perm:[1,0,3,2] row_mask:0xf bank_mask:0xf bound_ctrl:1
	v_add_f32_dpp v37, v37, v37 quad_perm:[1,0,3,2] row_mask:0xf bank_mask:0xf bound_ctrl:1
	s_nop 0
	v_add_f32_dpp v36, v36, v36 quad_perm:[2,3,0,1] row_mask:0xf bank_mask:0xf bound_ctrl:1
	v_add_f32_dpp v37, v37, v37 quad_perm:[2,3,0,1] row_mask:0xf bank_mask:0xf bound_ctrl:1
	s_nop 0
	v_add_f32_dpp v40, v36, v36 row_half_mirror row_mask:0xf bank_mask:0xf bound_ctrl:1
	v_add_f32_dpp v41, v37, v37 row_half_mirror row_mask:0xf bank_mask:0xf bound_ctrl:1
	s_waitcnt lgkmcnt(8)
	v_pk_mul_f32 v[36:37], v[158:159], v[40:41] op_sel_hi:[0,1]
	s_waitcnt lgkmcnt(2)
	v_pk_fma_f32 v[36:37], v[170:171], v[74:75], v[36:37] op_sel_hi:[0,1,1] neg_lo:[0,0,1] neg_hi:[0,0,1]
	v_pk_fma_f32 v[2:3], v[2:3], v[70:71], v[36:37] op_sel_hi:[1,0,1]
	v_pk_mul_f32 v[36:37], v[158:159], v[40:41] op_sel:[1,0]
	v_pk_mul_f32 v[38:39], v[160:161], v[40:41] op_sel_hi:[0,1]
	v_pk_fma_f32 v[36:37], v[170:171], v[74:75], v[36:37] op_sel:[1,0,0] neg_lo:[0,0,1] neg_hi:[0,0,1]
	v_pk_fma_f32 v[38:39], v[172:173], v[74:75], v[38:39] op_sel_hi:[0,1,1] neg_lo:[0,0,1] neg_hi:[0,0,1]
	v_pk_fma_f32 v[36:37], v[32:33], v[70:71], v[36:37] op_sel:[0,1,0]
	v_pk_fma_f32 v[38:39], v[34:35], v[72:73], v[38:39] op_sel_hi:[1,0,1]
	v_pk_mul_f32 v[70:71], v[160:161], v[40:41] op_sel:[1,0]
	v_pk_fma_f32 v[70:71], v[172:173], v[74:75], v[70:71] op_sel:[1,0,0] neg_lo:[0,0,1] neg_hi:[0,0,1]
	v_pk_fma_f32 v[42:43], v[178:179], v[36:37], 0 op_sel:[1,0,0] op_sel_hi:[1,1,0]
	v_pk_fma_f32 v[64:65], v[64:65], v[72:73], v[70:71] op_sel:[0,1,0]
	v_pk_fma_f32 v[34:35], v[180:181], v[64:65], v[42:43] op_sel:[1,0,0]
	v_pk_mul_f32 v[42:43], v[166:167], v[40:41] op_sel_hi:[0,1]
	v_pk_fma_f32 v[42:43], v[174:175], v[74:75], v[42:43] op_sel_hi:[0,1,1] neg_lo:[0,0,1] neg_hi:[0,0,1]
	v_pk_fma_f32 v[62:63], v[62:63], v[154:155], v[42:43] op_sel_hi:[1,0,1]
	v_pk_mul_f32 v[42:43], v[166:167], v[40:41] op_sel:[1,0]
	v_pk_fma_f32 v[42:43], v[174:175], v[74:75], v[42:43] op_sel:[1,0,0] neg_lo:[0,0,1] neg_hi:[0,0,1]
	v_pk_fma_f32 v[32:33], v[178:179], v[2:3], 0 op_sel_hi:[0,1,0]
	v_pk_fma_f32 v[60:61], v[60:61], v[154:155], v[42:43] op_sel:[0,1,0]
	v_pk_mul_f32 v[42:43], v[168:169], v[40:41] op_sel_hi:[0,1]
	v_pk_fma_f32 v[42:43], v[176:177], v[74:75], v[42:43] op_sel_hi:[0,1,1] neg_lo:[0,0,1] neg_hi:[0,0,1]
	v_pk_mul_f32 v[40:41], v[168:169], v[40:41] op_sel:[1,0]
	v_pk_fma_f32 v[32:33], v[180:181], v[38:39], v[32:33] op_sel_hi:[0,1,1]
	v_pk_fma_f32 v[66:67], v[66:67], v[156:157], v[42:43] op_sel_hi:[1,0,1]
	v_pk_fma_f32 v[40:41], v[176:177], v[74:75], v[40:41] op_sel:[1,0,0] neg_lo:[0,0,1] neg_hi:[0,0,1]
	v_pk_fma_f32 v[32:33], v[198:199], v[62:63], v[32:33] op_sel_hi:[0,1,1]
	v_pk_fma_f32 v[34:35], v[198:199], v[60:61], v[34:35] op_sel:[1,0,0]
	v_pk_fma_f32 v[68:69], v[68:69], v[156:157], v[40:41] op_sel:[0,1,0]
	v_pk_fma_f32 v[32:33], v[200:201], v[66:67], v[32:33] op_sel_hi:[0,1,1]
	v_pk_fma_f32 v[34:35], v[200:201], v[68:69], v[34:35] op_sel:[1,0,0]
	v_pk_add_f32 v[32:33], v[32:33], v[34:35]
	s_nop 1
	v_add_f32_dpp v32, v32, v32 quad_perm:[1,0,3,2] row_mask:0xf bank_mask:0xf bound_ctrl:1
	v_add_f32_dpp v33, v33, v33 quad_perm:[1,0,3,2] row_mask:0xf bank_mask:0xf bound_ctrl:1
	s_nop 0
	v_add_f32_dpp v32, v32, v32 quad_perm:[2,3,0,1] row_mask:0xf bank_mask:0xf bound_ctrl:1
	v_add_f32_dpp v33, v33, v33 quad_perm:[2,3,0,1] row_mask:0xf bank_mask:0xf bound_ctrl:1
	s_nop 0
	v_mov_b32_dpp v34, v32 row_half_mirror row_mask:0xf bank_mask:0xf bound_ctrl:1
	v_mov_b32_dpp v35, v33 row_half_mirror row_mask:0xf bank_mask:0xf bound_ctrl:1
	s_and_saveexec_b64 s[20:21], s[14:15]
	v_pk_add_f32 v[32:33], v[32:33], v[34:35]
	ds_write_b64 v153, v[32:33] offset:50944
	s_or_b64 exec, exec, s[20:21]
	s_waitcnt lgkmcnt(1)
	v_pk_mul_f32 v[202:203], v[46:47], v[38:39] op_sel_hi:[0,1]
	v_pk_fma_f32 v[202:203], v[44:45], v[2:3], v[202:203] op_sel_hi:[0,1,1]
	v_pk_mul_f32 v[46:47], v[46:47], v[64:65] op_sel:[1,0]
	v_pk_fma_f32 v[44:45], v[44:45], v[36:37], v[46:47] op_sel:[1,0,0]
	s_waitcnt lgkmcnt(0)
	v_pk_fma_f32 v[46:47], v[28:29], v[62:63], v[202:203] op_sel_hi:[0,1,1]
	v_pk_fma_f32 v[28:29], v[28:29], v[60:61], v[44:45] op_sel:[1,0,0]
	v_pk_fma_f32 v[44:45], v[30:31], v[66:67], v[46:47] op_sel_hi:[0,1,1]
	v_pk_fma_f32 v[28:29], v[30:31], v[68:69], v[28:29] op_sel:[1,0,0]
	v_pk_add_f32 v[28:29], v[44:45], v[28:29]
	ds_read_b128 v[70:73], v152 offset:6144
	ds_read_b128 v[154:157], v152 offset:6160
	ds_read_b128 v[158:161], v152 offset:10240
	ds_read_b128 v[166:169], v152 offset:10256
	ds_read_b128 v[170:173], v152 offset:14336
	ds_read_b128 v[174:177], v152 offset:14352
	ds_read_b128 v[178:181], v152 offset:18432
	ds_read_b128 v[198:201], v152 offset:18448
	ds_read_b64 v[74:75], v1 offset:22528
	ds_read_b128 v[40:43], v151 offset:2304
	ds_read_b128 v[32:35], v151 offset:2320
	v_add_f32_dpp v28, v28, v28 quad_perm:[1,0,3,2] row_mask:0xf bank_mask:0xf bound_ctrl:1
	v_add_f32_dpp v29, v29, v29 quad_perm:[1,0,3,2] row_mask:0xf bank_mask:0xf bound_ctrl:1
	s_nop 0
	v_add_f32_dpp v28, v28, v28 quad_perm:[2,3,0,1] row_mask:0xf bank_mask:0xf bound_ctrl:1
	v_add_f32_dpp v29, v29, v29 quad_perm:[2,3,0,1] row_mask:0xf bank_mask:0xf bound_ctrl:1
	s_nop 0
	v_add_f32_dpp v44, v28, v28 row_half_mirror row_mask:0xf bank_mask:0xf bound_ctrl:1
	v_add_f32_dpp v45, v29, v29 row_half_mirror row_mask:0xf bank_mask:0xf bound_ctrl:1
	s_waitcnt lgkmcnt(8)
	v_pk_mul_f32 v[28:29], v[158:159], v[44:45] op_sel_hi:[0,1]
	s_waitcnt lgkmcnt(2)
	v_pk_fma_f32 v[28:29], v[170:171], v[74:75], v[28:29] op_sel_hi:[0,1,1] neg_lo:[0,0,1] neg_hi:[0,0,1]
	v_pk_fma_f32 v[2:3], v[2:3], v[70:71], v[28:29] op_sel_hi:[1,0,1]
	v_pk_mul_f32 v[28:29], v[158:159], v[44:45] op_sel:[1,0]
	v_pk_mul_f32 v[30:31], v[160:161], v[44:45] op_sel_hi:[0,1]
	v_pk_fma_f32 v[28:29], v[170:171], v[74:75], v[28:29] op_sel:[1,0,0] neg_lo:[0,0,1] neg_hi:[0,0,1]
	v_pk_fma_f32 v[30:31], v[172:173], v[74:75], v[30:31] op_sel_hi:[0,1,1] neg_lo:[0,0,1] neg_hi:[0,0,1]
	v_pk_fma_f32 v[28:29], v[36:37], v[70:71], v[28:29] op_sel:[0,1,0]
	v_pk_fma_f32 v[30:31], v[38:39], v[72:73], v[30:31] op_sel_hi:[1,0,1]
	v_pk_mul_f32 v[70:71], v[160:161], v[44:45] op_sel:[1,0]
	v_pk_fma_f32 v[70:71], v[172:173], v[74:75], v[70:71] op_sel:[1,0,0] neg_lo:[0,0,1] neg_hi:[0,0,1]
	v_pk_fma_f32 v[46:47], v[178:179], v[28:29], 0 op_sel:[1,0,0] op_sel_hi:[1,1,0]
	v_pk_fma_f32 v[64:65], v[64:65], v[72:73], v[70:71] op_sel:[0,1,0]
	v_pk_fma_f32 v[38:39], v[180:181], v[64:65], v[46:47] op_sel:[1,0,0]
	v_pk_mul_f32 v[46:47], v[166:167], v[44:45] op_sel_hi:[0,1]
	v_pk_fma_f32 v[46:47], v[174:175], v[74:75], v[46:47] op_sel_hi:[0,1,1] neg_lo:[0,0,1] neg_hi:[0,0,1]
	v_pk_fma_f32 v[62:63], v[62:63], v[154:155], v[46:47] op_sel_hi:[1,0,1]
	v_pk_mul_f32 v[46:47], v[166:167], v[44:45] op_sel:[1,0]
	v_pk_fma_f32 v[46:47], v[174:175], v[74:75], v[46:47] op_sel:[1,0,0] neg_lo:[0,0,1] neg_hi:[0,0,1]
	v_pk_fma_f32 v[36:37], v[178:179], v[2:3], 0 op_sel_hi:[0,1,0]
	v_pk_fma_f32 v[60:61], v[60:61], v[154:155], v[46:47] op_sel:[0,1,0]
	v_pk_mul_f32 v[46:47], v[168:169], v[44:45] op_sel_hi:[0,1]
	v_pk_fma_f32 v[46:47], v[176:177], v[74:75], v[46:47] op_sel_hi:[0,1,1] neg_lo:[0,0,1] neg_hi:[0,0,1]
	v_pk_mul_f32 v[44:45], v[168:169], v[44:45] op_sel:[1,0]
	v_pk_fma_f32 v[36:37], v[180:181], v[30:31], v[36:37] op_sel_hi:[0,1,1]
	v_pk_fma_f32 v[66:67], v[66:67], v[156:157], v[46:47] op_sel_hi:[1,0,1]
	v_pk_fma_f32 v[44:45], v[176:177], v[74:75], v[44:45] op_sel:[1,0,0] neg_lo:[0,0,1] neg_hi:[0,0,1]
	v_pk_fma_f32 v[36:37], v[198:199], v[62:63], v[36:37] op_sel_hi:[0,1,1]
	v_pk_fma_f32 v[38:39], v[198:199], v[60:61], v[38:39] op_sel:[1,0,0]
	v_pk_fma_f32 v[68:69], v[68:69], v[156:157], v[44:45] op_sel:[0,1,0]
	v_pk_fma_f32 v[36:37], v[200:201], v[66:67], v[36:37] op_sel_hi:[0,1,1]
	v_pk_fma_f32 v[38:39], v[200:201], v[68:69], v[38:39] op_sel:[1,0,0]
	v_pk_add_f32 v[36:37], v[36:37], v[38:39]
	s_nop 1
	v_add_f32_dpp v36, v36, v36 quad_perm:[1,0,3,2] row_mask:0xf bank_mask:0xf bound_ctrl:1
	v_add_f32_dpp v37, v37, v37 quad_perm:[1,0,3,2] row_mask:0xf bank_mask:0xf bound_ctrl:1
	s_nop 0
	v_add_f32_dpp v36, v36, v36 quad_perm:[2,3,0,1] row_mask:0xf bank_mask:0xf bound_ctrl:1
	v_add_f32_dpp v37, v37, v37 quad_perm:[2,3,0,1] row_mask:0xf bank_mask:0xf bound_ctrl:1
	s_nop 0
	v_mov_b32_dpp v38, v36 row_half_mirror row_mask:0xf bank_mask:0xf bound_ctrl:1
	v_mov_b32_dpp v39, v37 row_half_mirror row_mask:0xf bank_mask:0xf bound_ctrl:1
	s_and_saveexec_b64 s[20:21], s[14:15]
	v_pk_add_f32 v[36:37], v[36:37], v[38:39]
	ds_write_b64 v153, v[36:37] offset:51200
	s_or_b64 exec, exec, s[20:21]
	s_waitcnt lgkmcnt(1)
	v_pk_mul_f32 v[202:203], v[42:43], v[30:31] op_sel_hi:[0,1]
	v_pk_fma_f32 v[202:203], v[40:41], v[2:3], v[202:203] op_sel_hi:[0,1,1]
	v_pk_mul_f32 v[42:43], v[42:43], v[64:65] op_sel:[1,0]
	v_pk_fma_f32 v[40:41], v[40:41], v[28:29], v[42:43] op_sel:[1,0,0]
	s_waitcnt lgkmcnt(0)
	v_pk_fma_f32 v[42:43], v[32:33], v[62:63], v[202:203] op_sel_hi:[0,1,1]
	v_pk_fma_f32 v[32:33], v[32:33], v[60:61], v[40:41] op_sel:[1,0,0]
	v_pk_fma_f32 v[40:41], v[34:35], v[66:67], v[42:43] op_sel_hi:[0,1,1]
	v_pk_fma_f32 v[32:33], v[34:35], v[68:69], v[32:33] op_sel:[1,0,0]
	v_pk_add_f32 v[32:33], v[40:41], v[32:33]
	ds_read_b128 v[70:73], v152 offset:6400
	ds_read_b128 v[154:157], v152 offset:6416
	ds_read_b128 v[158:161], v152 offset:10496
	ds_read_b128 v[166:169], v152 offset:10512
	ds_read_b128 v[170:173], v152 offset:14592
	ds_read_b128 v[174:177], v152 offset:14608
	ds_read_b128 v[178:181], v152 offset:18688
	ds_read_b128 v[198:201], v152 offset:18704
	ds_read_b64 v[74:75], v1 offset:22784
	ds_read_b128 v[44:47], v151 offset:2560
	ds_read_b128 v[36:39], v151 offset:2576
	v_add_f32_dpp v32, v32, v32 quad_perm:[1,0,3,2] row_mask:0xf bank_mask:0xf bound_ctrl:1
	v_add_f32_dpp v33, v33, v33 quad_perm:[1,0,3,2] row_mask:0xf bank_mask:0xf bound_ctrl:1
	s_nop 0
	v_add_f32_dpp v32, v32, v32 quad_perm:[2,3,0,1] row_mask:0xf bank_mask:0xf bound_ctrl:1
	v_add_f32_dpp v33, v33, v33 quad_perm:[2,3,0,1] row_mask:0xf bank_mask:0xf bound_ctrl:1
	s_nop 0
	v_add_f32_dpp v32, v32, v32 row_half_mirror row_mask:0xf bank_mask:0xf bound_ctrl:1
	v_add_f32_dpp v33, v33, v33 row_half_mirror row_mask:0xf bank_mask:0xf bound_ctrl:1
	s_waitcnt lgkmcnt(8)
	v_pk_mul_f32 v[34:35], v[158:159], v[32:33] op_sel_hi:[0,1]
	s_waitcnt lgkmcnt(2)
	v_pk_fma_f32 v[34:35], v[170:171], v[74:75], v[34:35] op_sel_hi:[0,1,1] neg_lo:[0,0,1] neg_hi:[0,0,1]
	v_pk_fma_f32 v[2:3], v[2:3], v[70:71], v[34:35] op_sel_hi:[1,0,1]
	v_pk_mul_f32 v[34:35], v[158:159], v[32:33] op_sel:[1,0]
	v_pk_mul_f32 v[42:43], v[160:161], v[32:33] op_sel_hi:[0,1]
	v_pk_fma_f32 v[34:35], v[170:171], v[74:75], v[34:35] op_sel:[1,0,0] neg_lo:[0,0,1] neg_hi:[0,0,1]
	v_pk_fma_f32 v[42:43], v[172:173], v[74:75], v[42:43] op_sel_hi:[0,1,1] neg_lo:[0,0,1] neg_hi:[0,0,1]
	v_pk_fma_f32 v[40:41], v[28:29], v[70:71], v[34:35] op_sel:[0,1,0]
	v_pk_fma_f32 v[42:43], v[30:31], v[72:73], v[42:43] op_sel_hi:[1,0,1]
	v_pk_mul_f32 v[70:71], v[160:161], v[32:33] op_sel:[1,0]
	v_pk_fma_f32 v[70:71], v[172:173], v[74:75], v[70:71] op_sel:[1,0,0] neg_lo:[0,0,1] neg_hi:[0,0,1]
	v_pk_fma_f32 v[34:35], v[178:179], v[40:41], 0 op_sel:[1,0,0] op_sel_hi:[1,1,0]
	v_pk_fma_f32 v[64:65], v[64:65], v[72:73], v[70:71] op_sel:[0,1,0]
	v_pk_fma_f32 v[30:31], v[180:181], v[64:65], v[34:35] op_sel:[1,0,0]
	v_pk_mul_f32 v[34:35], v[166:167], v[32:33] op_sel_hi:[0,1]
	v_pk_fma_f32 v[34:35], v[174:175], v[74:75], v[34:35] op_sel_hi:[0,1,1] neg_lo:[0,0,1] neg_hi:[0,0,1]
	v_pk_fma_f32 v[62:63], v[62:63], v[154:155], v[34:35] op_sel_hi:[1,0,1]
	v_pk_mul_f32 v[34:35], v[166:167], v[32:33] op_sel:[1,0]
	v_pk_fma_f32 v[28:29], v[178:179], v[2:3], 0 op_sel_hi:[0,1,0]
	v_pk_fma_f32 v[34:35], v[174:175], v[74:75], v[34:35] op_sel:[1,0,0] neg_lo:[0,0,1] neg_hi:[0,0,1]
	v_pk_fma_f32 v[60:61], v[60:61], v[154:155], v[34:35] op_sel:[0,1,0]
	v_pk_mul_f32 v[34:35], v[168:169], v[32:33] op_sel_hi:[0,1]
	v_pk_fma_f32 v[34:35], v[176:177], v[74:75], v[34:35] op_sel_hi:[0,1,1] neg_lo:[0,0,1] neg_hi:[0,0,1]
	v_pk_fma_f32 v[72:73], v[66:67], v[156:157], v[34:35] op_sel_hi:[1,0,1]
	v_pk_mul_f32 v[32:33], v[168:169], v[32:33] op_sel:[1,0]
	v_pk_fma_f32 v[28:29], v[180:181], v[42:43], v[28:29] op_sel_hi:[0,1,1]
	v_pk_fma_f32 v[32:33], v[176:177], v[74:75], v[32:33] op_sel:[1,0,0] neg_lo:[0,0,1] neg_hi:[0,0,1]
	v_pk_fma_f32 v[28:29], v[198:199], v[62:63], v[28:29] op_sel_hi:[0,1,1]
	v_pk_fma_f32 v[30:31], v[198:199], v[60:61], v[30:31] op_sel:[1,0,0]
	v_pk_fma_f32 v[74:75], v[68:69], v[156:157], v[32:33] op_sel:[0,1,0]
	v_pk_fma_f32 v[28:29], v[200:201], v[72:73], v[28:29] op_sel_hi:[0,1,1]
	v_pk_fma_f32 v[30:31], v[200:201], v[74:75], v[30:31] op_sel:[1,0,0]
	v_pk_add_f32 v[28:29], v[28:29], v[30:31]
	s_nop 1
	v_add_f32_dpp v28, v28, v28 quad_perm:[1,0,3,2] row_mask:0xf bank_mask:0xf bound_ctrl:1
	v_add_f32_dpp v29, v29, v29 quad_perm:[1,0,3,2] row_mask:0xf bank_mask:0xf bound_ctrl:1
	s_nop 0
	v_add_f32_dpp v28, v28, v28 quad_perm:[2,3,0,1] row_mask:0xf bank_mask:0xf bound_ctrl:1
	v_add_f32_dpp v29, v29, v29 quad_perm:[2,3,0,1] row_mask:0xf bank_mask:0xf bound_ctrl:1
	s_nop 0
	v_mov_b32_dpp v30, v28 row_half_mirror row_mask:0xf bank_mask:0xf bound_ctrl:1
	v_mov_b32_dpp v31, v29 row_half_mirror row_mask:0xf bank_mask:0xf bound_ctrl:1
	s_and_saveexec_b64 s[20:21], s[14:15]
	v_pk_add_f32 v[28:29], v[28:29], v[30:31]
	ds_write_b64 v153, v[28:29] offset:51456
	s_or_b64 exec, exec, s[20:21]
	s_waitcnt lgkmcnt(1)
	v_pk_mul_f32 v[66:67], v[46:47], v[42:43] op_sel_hi:[0,1]
	v_pk_fma_f32 v[66:67], v[44:45], v[2:3], v[66:67] op_sel_hi:[0,1,1]
	v_pk_mul_f32 v[46:47], v[46:47], v[64:65] op_sel:[1,0]
	v_pk_fma_f32 v[44:45], v[44:45], v[40:41], v[46:47] op_sel:[1,0,0]
	s_waitcnt lgkmcnt(0)
	v_pk_fma_f32 v[46:47], v[36:37], v[62:63], v[66:67] op_sel_hi:[0,1,1]
	v_pk_fma_f32 v[36:37], v[36:37], v[60:61], v[44:45] op_sel:[1,0,0]
	v_pk_fma_f32 v[44:45], v[38:39], v[72:73], v[46:47] op_sel_hi:[0,1,1]
	v_pk_fma_f32 v[36:37], v[38:39], v[74:75], v[36:37] op_sel:[1,0,0]
	v_pk_add_f32 v[36:37], v[44:45], v[36:37]
	ds_read_b128 v[154:157], v152 offset:6656
	ds_read_b128 v[158:161], v152 offset:6672
	ds_read_b128 v[166:169], v152 offset:10752
	ds_read_b128 v[170:173], v152 offset:10768
	ds_read_b128 v[174:177], v152 offset:14848
	ds_read_b128 v[178:181], v152 offset:14864
	ds_read_b128 v[198:201], v152 offset:18944
	ds_read_b128 v[202:205], v152 offset:18960
	ds_read_b64 v[206:207], v1 offset:23040
	ds_read_b128 v[32:35], v151 offset:2816
	ds_read_b128 v[28:31], v151 offset:2832
	v_add_f32_dpp v36, v36, v36 quad_perm:[1,0,3,2] row_mask:0xf bank_mask:0xf bound_ctrl:1
	v_add_f32_dpp v37, v37, v37 quad_perm:[1,0,3,2] row_mask:0xf bank_mask:0xf bound_ctrl:1
	s_nop 0
	s_waitcnt lgkmcnt(6)
	v_add_f32_dpp v36, v36, v36 quad_perm:[2,3,0,1] row_mask:0xf bank_mask:0xf bound_ctrl:1
	v_add_f32_dpp v37, v37, v37 quad_perm:[2,3,0,1] row_mask:0xf bank_mask:0xf bound_ctrl:1
	s_nop 0
	v_add_f32_dpp v36, v36, v36 row_half_mirror row_mask:0xf bank_mask:0xf bound_ctrl:1
	v_add_f32_dpp v37, v37, v37 row_half_mirror row_mask:0xf bank_mask:0xf bound_ctrl:1
	s_nop 0
	v_pk_mul_f32 v[38:39], v[166:167], v[36:37] op_sel_hi:[0,1]
	s_waitcnt lgkmcnt(2)
	v_pk_fma_f32 v[38:39], v[174:175], v[206:207], v[38:39] op_sel_hi:[0,1,1] neg_lo:[0,0,1] neg_hi:[0,0,1]
	v_pk_fma_f32 v[70:71], v[2:3], v[154:155], v[38:39] op_sel_hi:[1,0,1]
	v_pk_mul_f32 v[2:3], v[166:167], v[36:37] op_sel:[1,0]
	s_nop 0
	v_pk_fma_f32 v[2:3], v[174:175], v[206:207], v[2:3] op_sel:[1,0,0] neg_lo:[0,0,1] neg_hi:[0,0,1]
	s_nop 0
	v_pk_fma_f32 v[68:69], v[40:41], v[154:155], v[2:3] op_sel:[0,1,0]
	v_pk_mul_f32 v[40:41], v[168:169], v[36:37] op_sel_hi:[0,1]
	v_pk_fma_f32 v[40:41], v[176:177], v[206:207], v[40:41] op_sel_hi:[0,1,1] neg_lo:[0,0,1] neg_hi:[0,0,1]
	v_pk_fma_f32 v[66:67], v[42:43], v[156:157], v[40:41] op_sel_hi:[1,0,1]
	v_pk_mul_f32 v[42:43], v[168:169], v[36:37] op_sel:[1,0]
	v_pk_fma_f32 v[42:43], v[176:177], v[206:207], v[42:43] op_sel:[1,0,0] neg_lo:[0,0,1] neg_hi:[0,0,1]
	v_pk_fma_f32 v[38:39], v[198:199], v[68:69], 0 op_sel:[1,0,0] op_sel_hi:[1,1,0]
	v_pk_fma_f32 v[64:65], v[64:65], v[156:157], v[42:43] op_sel:[0,1,0]
	v_pk_fma_f32 v[38:39], v[200:201], v[64:65], v[38:39] op_sel:[1,0,0]
	v_pk_mul_f32 v[40:41], v[170:171], v[36:37] op_sel_hi:[0,1]
	v_pk_fma_f32 v[40:41], v[178:179], v[206:207], v[40:41] op_sel_hi:[0,1,1] neg_lo:[0,0,1] neg_hi:[0,0,1]
	v_pk_fma_f32 v[62:63], v[62:63], v[158:159], v[40:41] op_sel_hi:[1,0,1]
	v_pk_mul_f32 v[40:41], v[170:171], v[36:37] op_sel:[1,0]
	v_mov_b32_e32 v42, v173
	v_pk_fma_f32 v[40:41], v[178:179], v[206:207], v[40:41] op_sel:[1,0,0] neg_lo:[0,0,1] neg_hi:[0,0,1]
	v_pk_fma_f32 v[2:3], v[198:199], v[70:71], 0 op_sel_hi:[0,1,0]
	v_pk_fma_f32 v[60:61], v[60:61], v[158:159], v[40:41] op_sel:[0,1,0]
	v_pk_mul_f32 v[40:41], v[172:173], v[36:37] op_sel_hi:[0,1]
	v_pk_fma_f32 v[40:41], v[180:181], v[206:207], v[40:41] op_sel_hi:[0,1,1] neg_lo:[0,0,1] neg_hi:[0,0,1]
	v_pk_mul_f32 v[36:37], v[42:43], v[36:37] op_sel_hi:[0,1]
	v_pk_fma_f32 v[2:3], v[200:201], v[66:67], v[2:3] op_sel_hi:[0,1,1]
	v_pk_fma_f32 v[46:47], v[72:73], v[160:161], v[40:41] op_sel_hi:[1,0,1]
	v_mov_b32_e32 v40, v161
	v_pk_fma_f32 v[36:37], v[180:181], v[206:207], v[36:37] op_sel:[1,0,0] neg_lo:[0,0,1] neg_hi:[0,0,1]
	v_pk_fma_f32 v[2:3], v[202:203], v[62:63], v[2:3] op_sel_hi:[0,1,1]
	v_pk_fma_f32 v[38:39], v[202:203], v[60:61], v[38:39] op_sel:[1,0,0]
	v_pk_fma_f32 v[44:45], v[74:75], v[40:41], v[36:37] op_sel_hi:[1,0,1]
	v_pk_fma_f32 v[2:3], v[204:205], v[46:47], v[2:3] op_sel_hi:[0,1,1]
	v_pk_fma_f32 v[36:37], v[204:205], v[44:45], v[38:39] op_sel:[1,0,0]
	v_pk_add_f32 v[2:3], v[2:3], v[36:37]
	s_nop 1
	v_add_f32_dpp v2, v2, v2 quad_perm:[1,0,3,2] row_mask:0xf bank_mask:0xf bound_ctrl:1
	v_add_f32_dpp v3, v3, v3 quad_perm:[1,0,3,2] row_mask:0xf bank_mask:0xf bound_ctrl:1
	s_nop 0
	v_add_f32_dpp v2, v2, v2 quad_perm:[2,3,0,1] row_mask:0xf bank_mask:0xf bound_ctrl:1
	v_add_f32_dpp v3, v3, v3 quad_perm:[2,3,0,1] row_mask:0xf bank_mask:0xf bound_ctrl:1
	s_nop 0
	v_mov_b32_dpp v36, v2 row_half_mirror row_mask:0xf bank_mask:0xf bound_ctrl:1
	v_mov_b32_dpp v37, v3 row_half_mirror row_mask:0xf bank_mask:0xf bound_ctrl:1
	s_and_saveexec_b64 s[20:21], s[14:15]
	v_pk_add_f32 v[2:3], v[2:3], v[36:37]
	ds_write_b64 v153, v[2:3] offset:51712
	s_or_b64 exec, exec, s[20:21]

.LBB0_635:
	s_andn2_saveexec_b64 s[0:1], s[0:1]
	s_cbranch_execz .LBB0_576
	v_pk_mul_f32 v[2:3], v[66:67], v[34:35] op_sel_hi:[1,0]
	v_pk_fma_f32 v[2:3], v[70:71], v[32:33], v[2:3] op_sel_hi:[1,0,1]
	v_pk_mul_f32 v[34:35], v[64:65], v[34:35] op_sel:[0,1]
	v_pk_fma_f32 v[2:3], v[62:63], v[28:29], v[2:3] op_sel_hi:[1,0,1]
	v_pk_fma_f32 v[32:33], v[68:69], v[32:33], v[34:35] op_sel:[0,1,0]
	v_pk_fma_f32 v[2:3], v[46:47], v[30:31], v[2:3] op_sel_hi:[1,0,1]
	v_pk_fma_f32 v[28:29], v[60:61], v[28:29], v[32:33] op_sel:[0,1,0]
	v_pk_fma_f32 v[28:29], v[44:45], v[30:31], v[28:29] op_sel:[0,1,0]
	s_and_b32 s20, s25, 1
	v_pk_add_f32 v[2:3], v[2:3], v[28:29]
	s_mul_i32 s21, s20, 0x6000
	s_add_i32 s21, s21, 0
	v_add_f32_dpp v2, v2, v2 quad_perm:[1,0,3,2] row_mask:0xf bank_mask:0xf bound_ctrl:1
	v_add_f32_dpp v3, v3, v3 quad_perm:[1,0,3,2] row_mask:0xf bank_mask:0xf bound_ctrl:1
	s_lshl_b32 s22, s20, 12
	s_nop 0
	s_cmp_eq_u32 s20, 1
	v_lshl_add_u32 v1, v97, 2, s21
	v_add_f32_dpp v2, v2, v2 quad_perm:[2,3,0,1] row_mask:0xf bank_mask:0xf bound_ctrl:1
	v_add_f32_dpp v3, v3, v3 quad_perm:[2,3,0,1] row_mask:0xf bank_mask:0xf bound_ctrl:1
	s_cselect_b32 s20, 0x6000, 0
	s_nop 0
	v_lshl_add_u32 v73, v98, 2, s21
	v_add_u32_e32 v74, s20, v143
	ds_read_b128 v[152:155], v1 offset:6912
	ds_read_b128 v[156:159], v1 offset:6928
	ds_read_b128 v[166:169], v1 offset:11008
	ds_read_b128 v[170:173], v1 offset:11024
	ds_read_b128 v[174:177], v1 offset:15104
	ds_read_b128 v[178:181], v1 offset:15120
	ds_read_b128 v[198:201], v1 offset:19200
	ds_read_b128 v[202:205], v1 offset:19216
	ds_read_b64 v[160:161], v73 offset:23296
	ds_read_b128 v[40:43], v74 offset:3072
	ds_read_b128 v[36:39], v74 offset:3088
	v_add_f32_dpp v28, v2, v2 row_half_mirror row_mask:0xf bank_mask:0xf bound_ctrl:1
	v_add_f32_dpp v29, v3, v3 row_half_mirror row_mask:0xf bank_mask:0xf bound_ctrl:1
	s_waitcnt lgkmcnt(6)
	v_pk_mul_f32 v[2:3], v[166:167], v[28:29] op_sel_hi:[0,1]
	s_waitcnt lgkmcnt(2)
	v_pk_fma_f32 v[2:3], v[174:175], v[160:161], v[2:3] op_sel_hi:[0,1,1] neg_lo:[0,0,1] neg_hi:[0,0,1]
	v_pk_fma_f32 v[2:3], v[70:71], v[152:153], v[2:3] op_sel_hi:[1,0,1]
	v_pk_mul_f32 v[30:31], v[166:167], v[28:29] op_sel:[1,0]
	v_pk_mul_f32 v[34:35], v[168:169], v[28:29] op_sel_hi:[0,1]
	v_pk_fma_f32 v[30:31], v[174:175], v[160:161], v[30:31] op_sel:[1,0,0] neg_lo:[0,0,1] neg_hi:[0,0,1]
	v_pk_fma_f32 v[34:35], v[176:177], v[160:161], v[34:35] op_sel_hi:[0,1,1] neg_lo:[0,0,1] neg_hi:[0,0,1]
	v_pk_mul_f32 v[70:71], v[168:169], v[28:29] op_sel:[1,0]
	v_pk_fma_f32 v[68:69], v[68:69], v[152:153], v[30:31] op_sel:[0,1,0]
	v_pk_fma_f32 v[66:67], v[66:67], v[154:155], v[34:35] op_sel_hi:[1,0,1]
	v_pk_fma_f32 v[70:71], v[176:177], v[160:161], v[70:71] op_sel:[1,0,0] neg_lo:[0,0,1] neg_hi:[0,0,1]
	v_pk_fma_f32 v[32:33], v[198:199], v[68:69], 0 op_sel:[1,0,0] op_sel_hi:[1,1,0]
	v_pk_fma_f32 v[64:65], v[64:65], v[154:155], v[70:71] op_sel:[0,1,0]
	v_pk_fma_f32 v[32:33], v[200:201], v[64:65], v[32:33] op_sel:[1,0,0]
	v_pk_mul_f32 v[34:35], v[170:171], v[28:29] op_sel_hi:[0,1]
	v_pk_fma_f32 v[34:35], v[178:179], v[160:161], v[34:35] op_sel_hi:[0,1,1] neg_lo:[0,0,1] neg_hi:[0,0,1]
	v_pk_fma_f32 v[62:63], v[62:63], v[156:157], v[34:35] op_sel_hi:[1,0,1]
	v_pk_mul_f32 v[34:35], v[170:171], v[28:29] op_sel:[1,0]
	v_pk_fma_f32 v[30:31], v[198:199], v[2:3], 0 op_sel_hi:[0,1,0]
	v_pk_fma_f32 v[34:35], v[178:179], v[160:161], v[34:35] op_sel:[1,0,0] neg_lo:[0,0,1] neg_hi:[0,0,1]
	v_pk_fma_f32 v[60:61], v[60:61], v[156:157], v[34:35] op_sel:[0,1,0]
	v_pk_mul_f32 v[34:35], v[172:173], v[28:29] op_sel_hi:[0,1]
	v_pk_fma_f32 v[30:31], v[200:201], v[66:67], v[30:31] op_sel_hi:[0,1,1]
	v_pk_fma_f32 v[34:35], v[180:181], v[160:161], v[34:35] op_sel_hi:[0,1,1] neg_lo:[0,0,1] neg_hi:[0,0,1]
	v_pk_mul_f32 v[28:29], v[172:173], v[28:29] op_sel:[1,0]
	v_pk_fma_f32 v[30:31], v[202:203], v[62:63], v[30:31] op_sel_hi:[0,1,1]
	v_pk_fma_f32 v[46:47], v[46:47], v[158:159], v[34:35] op_sel_hi:[1,0,1]
	v_pk_fma_f32 v[28:29], v[180:181], v[160:161], v[28:29] op_sel:[1,0,0] neg_lo:[0,0,1] neg_hi:[0,0,1]
	v_pk_fma_f32 v[32:33], v[202:203], v[60:61], v[32:33] op_sel:[1,0,0]
	v_pk_fma_f32 v[44:45], v[44:45], v[158:159], v[28:29] op_sel:[0,1,0]
	v_pk_fma_f32 v[28:29], v[204:205], v[46:47], v[30:31] op_sel_hi:[0,1,1]
	v_pk_fma_f32 v[30:31], v[204:205], v[44:45], v[32:33] op_sel:[1,0,0]
	v_pk_add_f32 v[28:29], v[28:29], v[30:31]
	v_add_u32_e32 v72, s22, v99
	s_nop 0
	v_add_f32_dpp v28, v28, v28 quad_perm:[1,0,3,2] row_mask:0xf bank_mask:0xf bound_ctrl:1
	v_add_f32_dpp v29, v29, v29 quad_perm:[1,0,3,2] row_mask:0xf bank_mask:0xf bound_ctrl:1
	s_nop 0
	v_add_f32_dpp v28, v28, v28 quad_perm:[2,3,0,1] row_mask:0xf bank_mask:0xf bound_ctrl:1
	v_add_f32_dpp v29, v29, v29 quad_perm:[2,3,0,1] row_mask:0xf bank_mask:0xf bound_ctrl:1
	s_nop 0
	v_mov_b32_dpp v30, v28 row_half_mirror row_mask:0xf bank_mask:0xf bound_ctrl:1
	v_mov_b32_dpp v31, v29 row_half_mirror row_mask:0xf bank_mask:0xf bound_ctrl:1
	s_and_saveexec_b64 s[20:21], s[14:15]
	v_pk_add_f32 v[28:29], v[28:29], v[30:31]
	ds_write_b64 v72, v[28:29] offset:51968
	s_or_b64 exec, exec, s[20:21]
	s_waitcnt lgkmcnt(1)
	v_pk_mul_f32 v[160:161], v[42:43], v[66:67] op_sel_hi:[0,1]
	v_pk_fma_f32 v[160:161], v[40:41], v[2:3], v[160:161] op_sel_hi:[0,1,1]
	v_pk_mul_f32 v[42:43], v[42:43], v[64:65] op_sel:[1,0]
	v_pk_fma_f32 v[40:41], v[40:41], v[68:69], v[42:43] op_sel:[1,0,0]
	s_waitcnt lgkmcnt(0)
	v_pk_fma_f32 v[42:43], v[36:37], v[62:63], v[160:161] op_sel_hi:[0,1,1]
	v_pk_fma_f32 v[36:37], v[36:37], v[60:61], v[40:41] op_sel:[1,0,0]
	v_pk_fma_f32 v[40:41], v[38:39], v[46:47], v[42:43] op_sel_hi:[0,1,1]
	v_pk_fma_f32 v[36:37], v[38:39], v[44:45], v[36:37] op_sel:[1,0,0]
	v_pk_add_f32 v[36:37], v[40:41], v[36:37]
	ds_read_b128 v[152:155], v1 offset:7168
	ds_read_b128 v[156:159], v1 offset:7184
	ds_read_b128 v[166:169], v1 offset:11264
	ds_read_b128 v[170:173], v1 offset:11280
	ds_read_b128 v[174:177], v1 offset:15360
	ds_read_b128 v[178:181], v1 offset:15376
	ds_read_b128 v[198:201], v1 offset:19456
	ds_read_b128 v[202:205], v1 offset:19472
	ds_read_b64 v[70:71], v73 offset:23552
	ds_read_b128 v[32:35], v74 offset:3328
	ds_read_b128 v[28:31], v74 offset:3344
	v_add_f32_dpp v36, v36, v36 quad_perm:[1,0,3,2] row_mask:0xf bank_mask:0xf bound_ctrl:1
	v_add_f32_dpp v37, v37, v37 quad_perm:[1,0,3,2] row_mask:0xf bank_mask:0xf bound_ctrl:1
	s_nop 0
	v_add_f32_dpp v36, v36, v36 quad_perm:[2,3,0,1] row_mask:0xf bank_mask:0xf bound_ctrl:1
	v_add_f32_dpp v37, v37, v37 quad_perm:[2,3,0,1] row_mask:0xf bank_mask:0xf bound_ctrl:1
	s_nop 0
	v_add_f32_dpp v36, v36, v36 row_half_mirror row_mask:0xf bank_mask:0xf bound_ctrl:1
	v_add_f32_dpp v37, v37, v37 row_half_mirror row_mask:0xf bank_mask:0xf bound_ctrl:1
	s_waitcnt lgkmcnt(8)
	v_pk_mul_f32 v[38:39], v[166:167], v[36:37] op_sel_hi:[0,1]
	s_waitcnt lgkmcnt(2)
	v_pk_fma_f32 v[38:39], v[174:175], v[70:71], v[38:39] op_sel_hi:[0,1,1] neg_lo:[0,0,1] neg_hi:[0,0,1]
	v_pk_fma_f32 v[2:3], v[2:3], v[152:153], v[38:39] op_sel_hi:[1,0,1]
	v_pk_mul_f32 v[38:39], v[166:167], v[36:37] op_sel:[1,0]
	v_pk_mul_f32 v[42:43], v[168:169], v[36:37] op_sel_hi:[0,1]
	v_pk_fma_f32 v[38:39], v[174:175], v[70:71], v[38:39] op_sel:[1,0,0] neg_lo:[0,0,1] neg_hi:[0,0,1]
	v_pk_fma_f32 v[42:43], v[176:177], v[70:71], v[42:43] op_sel_hi:[0,1,1] neg_lo:[0,0,1] neg_hi:[0,0,1]
	v_pk_fma_f32 v[68:69], v[68:69], v[152:153], v[38:39] op_sel:[0,1,0]
	v_pk_fma_f32 v[66:67], v[66:67], v[154:155], v[42:43] op_sel_hi:[1,0,1]
	v_pk_mul_f32 v[152:153], v[168:169], v[36:37] op_sel:[1,0]
	v_pk_fma_f32 v[152:153], v[176:177], v[70:71], v[152:153] op_sel:[1,0,0] neg_lo:[0,0,1] neg_hi:[0,0,1]
	v_pk_fma_f32 v[40:41], v[198:199], v[68:69], 0 op_sel:[1,0,0] op_sel_hi:[1,1,0]
	v_pk_fma_f32 v[64:65], v[64:65], v[154:155], v[152:153] op_sel:[0,1,0]
	v_pk_fma_f32 v[40:41], v[200:201], v[64:65], v[40:41] op_sel:[1,0,0]
	v_pk_mul_f32 v[42:43], v[170:171], v[36:37] op_sel_hi:[0,1]
	v_pk_fma_f32 v[42:43], v[178:179], v[70:71], v[42:43] op_sel_hi:[0,1,1] neg_lo:[0,0,1] neg_hi:[0,0,1]
	v_pk_fma_f32 v[62:63], v[62:63], v[156:157], v[42:43] op_sel_hi:[1,0,1]
	v_pk_mul_f32 v[42:43], v[170:171], v[36:37] op_sel:[1,0]
	v_pk_fma_f32 v[38:39], v[198:199], v[2:3], 0 op_sel_hi:[0,1,0]
	v_pk_fma_f32 v[42:43], v[178:179], v[70:71], v[42:43] op_sel:[1,0,0] neg_lo:[0,0,1] neg_hi:[0,0,1]
	v_pk_fma_f32 v[60:61], v[60:61], v[156:157], v[42:43] op_sel:[0,1,0]
	v_pk_mul_f32 v[42:43], v[172:173], v[36:37] op_sel_hi:[0,1]
	v_pk_fma_f32 v[38:39], v[200:201], v[66:67], v[38:39] op_sel_hi:[0,1,1]
	v_pk_fma_f32 v[42:43], v[180:181], v[70:71], v[42:43] op_sel_hi:[0,1,1] neg_lo:[0,0,1] neg_hi:[0,0,1]
	v_pk_mul_f32 v[36:37], v[172:173], v[36:37] op_sel:[1,0]
	v_pk_fma_f32 v[38:39], v[202:203], v[62:63], v[38:39] op_sel_hi:[0,1,1]
	v_pk_fma_f32 v[46:47], v[46:47], v[158:159], v[42:43] op_sel_hi:[1,0,1]
	v_pk_fma_f32 v[36:37], v[180:181], v[70:71], v[36:37] op_sel:[1,0,0] neg_lo:[0,0,1] neg_hi:[0,0,1]
	v_pk_fma_f32 v[40:41], v[202:203], v[60:61], v[40:41] op_sel:[1,0,0]
	v_pk_fma_f32 v[44:45], v[44:45], v[158:159], v[36:37] op_sel:[0,1,0]
	v_pk_fma_f32 v[36:37], v[204:205], v[46:47], v[38:39] op_sel_hi:[0,1,1]
	v_pk_fma_f32 v[38:39], v[204:205], v[44:45], v[40:41] op_sel:[1,0,0]
	v_pk_add_f32 v[36:37], v[36:37], v[38:39]
	s_nop 1
	v_add_f32_dpp v36, v36, v36 quad_perm:[1,0,3,2] row_mask:0xf bank_mask:0xf bound_ctrl:1
	v_add_f32_dpp v37, v37, v37 quad_perm:[1,0,3,2] row_mask:0xf bank_mask:0xf bound_ctrl:1
	s_nop 0
	v_add_f32_dpp v36, v36, v36 quad_perm:[2,3,0,1] row_mask:0xf bank_mask:0xf bound_ctrl:1
	v_add_f32_dpp v37, v37, v37 quad_perm:[2,3,0,1] row_mask:0xf bank_mask:0xf bound_ctrl:1
	s_nop 0
	v_mov_b32_dpp v38, v36 row_half_mirror row_mask:0xf bank_mask:0xf bound_ctrl:1
	v_mov_b32_dpp v39, v37 row_half_mirror row_mask:0xf bank_mask:0xf bound_ctrl:1
	s_and_saveexec_b64 s[20:21], s[14:15]
	v_pk_add_f32 v[36:37], v[36:37], v[38:39]
	ds_write_b64 v72, v[36:37] offset:52224
	s_or_b64 exec, exec, s[20:21]
	s_waitcnt lgkmcnt(1)
	v_pk_mul_f32 v[160:161], v[34:35], v[66:67] op_sel_hi:[0,1]
	v_pk_fma_f32 v[160:161], v[32:33], v[2:3], v[160:161] op_sel_hi:[0,1,1]
	v_pk_mul_f32 v[34:35], v[34:35], v[64:65] op_sel:[1,0]
	v_pk_fma_f32 v[32:33], v[32:33], v[68:69], v[34:35] op_sel:[1,0,0]
	s_waitcnt lgkmcnt(0)
	v_pk_fma_f32 v[34:35], v[28:29], v[62:63], v[160:161] op_sel_hi:[0,1,1]
	v_pk_fma_f32 v[28:29], v[28:29], v[60:61], v[32:33] op_sel:[1,0,0]
	v_pk_fma_f32 v[32:33], v[30:31], v[46:47], v[34:35] op_sel_hi:[0,1,1]
	v_pk_fma_f32 v[28:29], v[30:31], v[44:45], v[28:29] op_sel:[1,0,0]
	v_pk_add_f32 v[28:29], v[32:33], v[28:29]
	ds_read_b128 v[152:155], v1 offset:7424
	ds_read_b128 v[156:159], v1 offset:7440
	ds_read_b128 v[166:169], v1 offset:11520
	ds_read_b128 v[170:173], v1 offset:11536
	ds_read_b128 v[174:177], v1 offset:15616
	ds_read_b128 v[178:181], v1 offset:15632
	ds_read_b128 v[198:201], v1 offset:19712
	ds_read_b128 v[202:205], v1 offset:19728
	ds_read_b64 v[70:71], v73 offset:23808
	ds_read_b128 v[40:43], v74 offset:3584
	ds_read_b128 v[36:39], v74 offset:3600
	v_add_f32_dpp v28, v28, v28 quad_perm:[1,0,3,2] row_mask:0xf bank_mask:0xf bound_ctrl:1
	v_add_f32_dpp v29, v29, v29 quad_perm:[1,0,3,2] row_mask:0xf bank_mask:0xf bound_ctrl:1
	s_nop 0
	v_add_f32_dpp v28, v28, v28 quad_perm:[2,3,0,1] row_mask:0xf bank_mask:0xf bound_ctrl:1
	v_add_f32_dpp v29, v29, v29 quad_perm:[2,3,0,1] row_mask:0xf bank_mask:0xf bound_ctrl:1
	s_nop 0
	v_add_f32_dpp v28, v28, v28 row_half_mirror row_mask:0xf bank_mask:0xf bound_ctrl:1
	v_add_f32_dpp v29, v29, v29 row_half_mirror row_mask:0xf bank_mask:0xf bound_ctrl:1
	s_waitcnt lgkmcnt(8)
	v_pk_mul_f32 v[30:31], v[166:167], v[28:29] op_sel_hi:[0,1]
	s_waitcnt lgkmcnt(2)
	v_pk_fma_f32 v[30:31], v[174:175], v[70:71], v[30:31] op_sel_hi:[0,1,1] neg_lo:[0,0,1] neg_hi:[0,0,1]
	v_pk_fma_f32 v[2:3], v[2:3], v[152:153], v[30:31] op_sel_hi:[1,0,1]
	v_pk_mul_f32 v[30:31], v[166:167], v[28:29] op_sel:[1,0]
	v_pk_mul_f32 v[34:35], v[168:169], v[28:29] op_sel_hi:[0,1]
	v_pk_fma_f32 v[30:31], v[174:175], v[70:71], v[30:31] op_sel:[1,0,0] neg_lo:[0,0,1] neg_hi:[0,0,1]
	v_pk_fma_f32 v[34:35], v[176:177], v[70:71], v[34:35] op_sel_hi:[0,1,1] neg_lo:[0,0,1] neg_hi:[0,0,1]
	v_pk_fma_f32 v[68:69], v[68:69], v[152:153], v[30:31] op_sel:[0,1,0]
	v_pk_fma_f32 v[66:67], v[66:67], v[154:155], v[34:35] op_sel_hi:[1,0,1]
	v_pk_mul_f32 v[152:153], v[168:169], v[28:29] op_sel:[1,0]
	v_pk_fma_f32 v[152:153], v[176:177], v[70:71], v[152:153] op_sel:[1,0,0] neg_lo:[0,0,1] neg_hi:[0,0,1]
	v_pk_fma_f32 v[32:33], v[198:199], v[68:69], 0 op_sel:[1,0,0] op_sel_hi:[1,1,0]
	v_pk_fma_f32 v[64:65], v[64:65], v[154:155], v[152:153] op_sel:[0,1,0]
	v_pk_fma_f32 v[32:33], v[200:201], v[64:65], v[32:33] op_sel:[1,0,0]
	v_pk_mul_f32 v[34:35], v[170:171], v[28:29] op_sel_hi:[0,1]
	v_pk_fma_f32 v[34:35], v[178:179], v[70:71], v[34:35] op_sel_hi:[0,1,1] neg_lo:[0,0,1] neg_hi:[0,0,1]
	v_pk_fma_f32 v[62:63], v[62:63], v[156:157], v[34:35] op_sel_hi:[1,0,1]
	v_pk_mul_f32 v[34:35], v[170:171], v[28:29] op_sel:[1,0]
	v_pk_fma_f32 v[30:31], v[198:199], v[2:3], 0 op_sel_hi:[0,1,0]
	v_pk_fma_f32 v[34:35], v[178:179], v[70:71], v[34:35] op_sel:[1,0,0] neg_lo:[0,0,1] neg_hi:[0,0,1]
	v_pk_fma_f32 v[60:61], v[60:61], v[156:157], v[34:35] op_sel:[0,1,0]
	v_pk_mul_f32 v[34:35], v[172:173], v[28:29] op_sel_hi:[0,1]
	v_pk_fma_f32 v[30:31], v[200:201], v[66:67], v[30:31] op_sel_hi:[0,1,1]
	v_pk_fma_f32 v[34:35], v[180:181], v[70:71], v[34:35] op_sel_hi:[0,1,1] neg_lo:[0,0,1] neg_hi:[0,0,1]
	v_pk_mul_f32 v[28:29], v[172:173], v[28:29] op_sel:[1,0]
	v_pk_fma_f32 v[30:31], v[202:203], v[62:63], v[30:31] op_sel_hi:[0,1,1]
	v_pk_fma_f32 v[46:47], v[46:47], v[158:159], v[34:35] op_sel_hi:[1,0,1]
	v_pk_fma_f32 v[28:29], v[180:181], v[70:71], v[28:29] op_sel:[1,0,0] neg_lo:[0,0,1] neg_hi:[0,0,1]
	v_pk_fma_f32 v[32:33], v[202:203], v[60:61], v[32:33] op_sel:[1,0,0]
	v_pk_fma_f32 v[44:45], v[44:45], v[158:159], v[28:29] op_sel:[0,1,0]
	v_pk_fma_f32 v[28:29], v[204:205], v[46:47], v[30:31] op_sel_hi:[0,1,1]
	v_pk_fma_f32 v[30:31], v[204:205], v[44:45], v[32:33] op_sel:[1,0,0]
	v_pk_add_f32 v[28:29], v[28:29], v[30:31]
	s_nop 1
	v_add_f32_dpp v28, v28, v28 quad_perm:[1,0,3,2] row_mask:0xf bank_mask:0xf bound_ctrl:1
	v_add_f32_dpp v29, v29, v29 quad_perm:[1,0,3,2] row_mask:0xf bank_mask:0xf bound_ctrl:1
	s_nop 0
	v_add_f32_dpp v28, v28, v28 quad_perm:[2,3,0,1] row_mask:0xf bank_mask:0xf bound_ctrl:1
	v_add_f32_dpp v29, v29, v29 quad_perm:[2,3,0,1] row_mask:0xf bank_mask:0xf bound_ctrl:1
	s_nop 0
	v_mov_b32_dpp v30, v28 row_half_mirror row_mask:0xf bank_mask:0xf bound_ctrl:1
	v_mov_b32_dpp v31, v29 row_half_mirror row_mask:0xf bank_mask:0xf bound_ctrl:1
	s_and_saveexec_b64 s[20:21], s[14:15]
	v_pk_add_f32 v[28:29], v[28:29], v[30:31]
	ds_write_b64 v72, v[28:29] offset:52480
	s_or_b64 exec, exec, s[20:21]
	ds_read_b128 v[152:155], v1 offset:7680
	ds_read_b128 v[156:159], v1 offset:7696
	ds_read_b128 v[166:169], v1 offset:11776
	ds_read_b128 v[170:173], v1 offset:11792
	ds_read_b128 v[174:177], v1 offset:15872
	ds_read_b128 v[178:181], v1 offset:15888
	ds_read_b128 v[198:201], v1 offset:19968
	ds_read_b128 v[202:205], v1 offset:19984
	ds_read_b64 v[70:71], v73 offset:24064
	ds_read_b128 v[32:35], v74 offset:3840
	ds_read_b128 v[28:31], v74 offset:3856
	s_waitcnt lgkmcnt(12)
	v_pk_mul_f32 v[74:75], v[42:43], v[66:67] op_sel_hi:[0,1]
	v_pk_fma_f32 v[74:75], v[40:41], v[2:3], v[74:75] op_sel_hi:[0,1,1]
	v_pk_mul_f32 v[42:43], v[42:43], v[64:65] op_sel:[1,0]
	v_pk_fma_f32 v[40:41], v[40:41], v[68:69], v[42:43] op_sel:[1,0,0]
	s_waitcnt lgkmcnt(11)
	v_pk_fma_f32 v[42:43], v[36:37], v[62:63], v[74:75] op_sel_hi:[0,1,1]
	v_pk_fma_f32 v[36:37], v[36:37], v[60:61], v[40:41] op_sel:[1,0,0]
	v_pk_fma_f32 v[40:41], v[38:39], v[46:47], v[42:43] op_sel_hi:[0,1,1]
	v_pk_fma_f32 v[36:37], v[38:39], v[44:45], v[36:37] op_sel:[1,0,0]
	v_pk_add_f32 v[36:37], v[40:41], v[36:37]
	s_waitcnt lgkmcnt(10)
	s_nop 0
	v_add_f32_dpp v36, v36, v36 quad_perm:[1,0,3,2] row_mask:0xf bank_mask:0xf bound_ctrl:1
	v_add_f32_dpp v37, v37, v37 quad_perm:[1,0,3,2] row_mask:0xf bank_mask:0xf bound_ctrl:1
	s_nop 0
	v_add_f32_dpp v36, v36, v36 quad_perm:[2,3,0,1] row_mask:0xf bank_mask:0xf bound_ctrl:1
	v_add_f32_dpp v37, v37, v37 quad_perm:[2,3,0,1] row_mask:0xf bank_mask:0xf bound_ctrl:1
	s_nop 0
	v_add_f32_dpp v74, v36, v36 row_half_mirror row_mask:0xf bank_mask:0xf bound_ctrl:1
	v_add_f32_dpp v75, v37, v37 row_half_mirror row_mask:0xf bank_mask:0xf bound_ctrl:1
	s_waitcnt lgkmcnt(8)
	v_pk_mul_f32 v[36:37], v[166:167], v[74:75] op_sel_hi:[0,1]
	s_waitcnt lgkmcnt(2)
	v_pk_fma_f32 v[36:37], v[174:175], v[70:71], v[36:37] op_sel_hi:[0,1,1] neg_lo:[0,0,1] neg_hi:[0,0,1]
	v_pk_mul_f32 v[38:39], v[168:169], v[74:75] op_sel_hi:[0,1]
	v_pk_fma_f32 v[2:3], v[2:3], v[152:153], v[36:37] op_sel_hi:[1,0,1]
	v_pk_mul_f32 v[36:37], v[166:167], v[74:75] op_sel:[1,0]
	v_pk_fma_f32 v[38:39], v[176:177], v[70:71], v[38:39] op_sel_hi:[0,1,1] neg_lo:[0,0,1] neg_hi:[0,0,1]
	v_pk_fma_f32 v[36:37], v[174:175], v[70:71], v[36:37] op_sel:[1,0,0] neg_lo:[0,0,1] neg_hi:[0,0,1]
	v_pk_fma_f32 v[38:39], v[66:67], v[154:155], v[38:39] op_sel_hi:[1,0,1]
	v_pk_fma_f32 v[36:37], v[68:69], v[152:153], v[36:37] op_sel:[0,1,0]
	v_pk_mul_f32 v[66:67], v[168:169], v[74:75] op_sel:[1,0]
	v_pk_fma_f32 v[42:43], v[198:199], v[2:3], 0 op_sel_hi:[0,1,0]
	v_pk_fma_f32 v[66:67], v[176:177], v[70:71], v[66:67] op_sel:[1,0,0] neg_lo:[0,0,1] neg_hi:[0,0,1]
	v_pk_fma_f32 v[68:69], v[198:199], v[36:37], 0 op_sel:[1,0,0] op_sel_hi:[1,1,0]
	v_pk_fma_f32 v[40:41], v[64:65], v[154:155], v[66:67] op_sel:[0,1,0]
	v_pk_fma_f32 v[64:65], v[200:201], v[38:39], v[42:43] op_sel_hi:[0,1,1]
	v_pk_fma_f32 v[66:67], v[200:201], v[40:41], v[68:69] op_sel:[1,0,0]
	v_pk_mul_f32 v[42:43], v[170:171], v[74:75] op_sel_hi:[0,1]
	v_pk_fma_f32 v[42:43], v[178:179], v[70:71], v[42:43] op_sel_hi:[0,1,1] neg_lo:[0,0,1] neg_hi:[0,0,1]
	v_pk_fma_f32 v[42:43], v[62:63], v[156:157], v[42:43] op_sel_hi:[1,0,1]
	v_pk_mul_f32 v[62:63], v[170:171], v[74:75] op_sel:[1,0]
	v_pk_fma_f32 v[62:63], v[178:179], v[70:71], v[62:63] op_sel:[1,0,0] neg_lo:[0,0,1] neg_hi:[0,0,1]
	v_pk_fma_f32 v[60:61], v[60:61], v[156:157], v[62:63] op_sel:[0,1,0]
	v_pk_fma_f32 v[62:63], v[202:203], v[42:43], v[64:65] op_sel_hi:[0,1,1]
	v_pk_fma_f32 v[64:65], v[202:203], v[60:61], v[66:67] op_sel:[1,0,0]
	v_pk_mul_f32 v[66:67], v[172:173], v[74:75] op_sel_hi:[0,1]
	v_pk_fma_f32 v[66:67], v[180:181], v[70:71], v[66:67] op_sel_hi:[0,1,1] neg_lo:[0,0,1] neg_hi:[0,0,1]
	v_pk_mul_f32 v[68:69], v[172:173], v[74:75] op_sel:[1,0]
	v_pk_fma_f32 v[46:47], v[46:47], v[158:159], v[66:67] op_sel_hi:[1,0,1]
	v_pk_fma_f32 v[68:69], v[180:181], v[70:71], v[68:69] op_sel:[1,0,0] neg_lo:[0,0,1] neg_hi:[0,0,1]
	v_pk_fma_f32 v[44:45], v[44:45], v[158:159], v[68:69] op_sel:[0,1,0]
	v_pk_fma_f32 v[62:63], v[204:205], v[46:47], v[62:63] op_sel_hi:[0,1,1]
	v_pk_fma_f32 v[64:65], v[204:205], v[44:45], v[64:65] op_sel:[1,0,0]
	v_pk_add_f32 v[62:63], v[62:63], v[64:65]
	s_nop 1
	v_add_f32_dpp v62, v62, v62 quad_perm:[1,0,3,2] row_mask:0xf bank_mask:0xf bound_ctrl:1
	v_add_f32_dpp v63, v63, v63 quad_perm:[1,0,3,2] row_mask:0xf bank_mask:0xf bound_ctrl:1
	s_nop 0
	v_add_f32_dpp v62, v62, v62 quad_perm:[2,3,0,1] row_mask:0xf bank_mask:0xf bound_ctrl:1
	v_add_f32_dpp v63, v63, v63 quad_perm:[2,3,0,1] row_mask:0xf bank_mask:0xf bound_ctrl:1
	s_nop 0
	v_mov_b32_dpp v64, v62 row_half_mirror row_mask:0xf bank_mask:0xf bound_ctrl:1
	v_mov_b32_dpp v65, v63 row_half_mirror row_mask:0xf bank_mask:0xf bound_ctrl:1
	s_and_saveexec_b64 s[20:21], s[14:15]
	v_pk_add_f32 v[62:63], v[62:63], v[64:65]
	ds_write_b64 v72, v[62:63] offset:52736
	s_or_b64 exec, exec, s[20:21]
	s_waitcnt lgkmcnt(1)
	v_pk_mul_f32 v[66:67], v[34:35], v[38:39] op_sel_hi:[0,1]
	v_pk_mul_f32 v[68:69], v[34:35], v[40:41] op_sel:[1,0]
	v_pk_fma_f32 v[66:67], v[32:33], v[2:3], v[66:67] op_sel_hi:[0,1,1]
	v_pk_fma_f32 v[68:69], v[32:33], v[36:37], v[68:69] op_sel:[1,0,0]
	s_waitcnt lgkmcnt(0)
	v_pk_fma_f32 v[66:67], v[28:29], v[42:43], v[66:67] op_sel_hi:[0,1,1]
	v_pk_fma_f32 v[68:69], v[28:29], v[60:61], v[68:69] op_sel:[1,0,0]
	v_pk_fma_f32 v[66:67], v[30:31], v[46:47], v[66:67] op_sel_hi:[0,1,1]
	v_pk_fma_f32 v[68:69], v[30:31], v[44:45], v[68:69] op_sel:[1,0,0]
	v_pk_add_f32 v[66:67], v[66:67], v[68:69]
	ds_read_b64 v[74:75], v73 offset:24320
	ds_read_b128 v[152:155], v1 offset:20240
	ds_read_b128 v[156:159], v1 offset:20224
	ds_read_b128 v[166:169], v1 offset:16144
	ds_read_b128 v[62:65], v1 offset:16128
	ds_read_b128 v[170:173], v1 offset:12048
	ds_read_b128 v[174:177], v1 offset:12032
	ds_read_b128 v[178:181], v1 offset:7936
	ds_read_b128 v[198:201], v1 offset:7952
	v_add_f32_dpp v66, v66, v66 quad_perm:[1,0,3,2] row_mask:0xf bank_mask:0xf bound_ctrl:1
	v_add_f32_dpp v67, v67, v67 quad_perm:[1,0,3,2] row_mask:0xf bank_mask:0xf bound_ctrl:1
	s_nop 0
	v_add_f32_dpp v66, v66, v66 quad_perm:[2,3,0,1] row_mask:0xf bank_mask:0xf bound_ctrl:1
	v_add_f32_dpp v67, v67, v67 quad_perm:[2,3,0,1] row_mask:0xf bank_mask:0xf bound_ctrl:1
	s_nop 0
	v_add_f32_dpp v160, v66, v66 row_half_mirror row_mask:0xf bank_mask:0xf bound_ctrl:1
	v_add_f32_dpp v161, v67, v67 row_half_mirror row_mask:0xf bank_mask:0xf bound_ctrl:1
	s_waitcnt lgkmcnt(2)
	v_pk_mul_f32 v[66:67], v[174:175], v[160:161] op_sel_hi:[0,1]
	v_pk_fma_f32 v[66:67], v[74:75], v[62:63], v[66:67] op_sel_hi:[1,0,1] neg_lo:[0,0,1] neg_hi:[0,0,1]
	s_waitcnt lgkmcnt(1)
	v_pk_fma_f32 v[70:71], v[2:3], v[178:179], v[66:67] op_sel_hi:[1,0,1]
	v_pk_mul_f32 v[2:3], v[174:175], v[160:161] op_sel:[1,0]
	s_nop 0
	v_pk_fma_f32 v[2:3], v[74:75], v[62:63], v[2:3] op_sel:[0,1,0] neg_lo:[0,0,1] neg_hi:[0,0,1]
	v_pk_mul_f32 v[62:63], v[176:177], v[160:161] op_sel_hi:[0,1]
	v_pk_fma_f32 v[62:63], v[74:75], v[64:65], v[62:63] op_sel_hi:[1,0,1] neg_lo:[0,0,1] neg_hi:[0,0,1]
	v_pk_fma_f32 v[66:67], v[38:39], v[180:181], v[62:63] op_sel_hi:[1,0,1]
	v_pk_mul_f32 v[62:63], v[176:177], v[160:161] op_sel:[1,0]
	v_pk_fma_f32 v[68:69], v[36:37], v[178:179], v[2:3] op_sel:[0,1,0]
	v_pk_fma_f32 v[62:63], v[74:75], v[64:65], v[62:63] op_sel:[0,1,0] neg_lo:[0,0,1] neg_hi:[0,0,1]
	v_pk_fma_f32 v[36:37], v[156:157], v[68:69], 0 op_sel:[1,0,0] op_sel_hi:[1,1,0]
	v_pk_fma_f32 v[64:65], v[40:41], v[180:181], v[62:63] op_sel:[0,1,0]
	v_pk_fma_f32 v[36:37], v[158:159], v[64:65], v[36:37] op_sel:[1,0,0]
	v_pk_mul_f32 v[38:39], v[170:171], v[160:161] op_sel_hi:[0,1]
	v_pk_fma_f32 v[38:39], v[74:75], v[166:167], v[38:39] op_sel_hi:[1,0,1] neg_lo:[0,0,1] neg_hi:[0,0,1]
	s_waitcnt lgkmcnt(0)
	v_pk_fma_f32 v[62:63], v[42:43], v[198:199], v[38:39] op_sel_hi:[1,0,1]
	v_pk_mul_f32 v[38:39], v[170:171], v[160:161] op_sel:[1,0]
	v_pk_fma_f32 v[2:3], v[156:157], v[70:71], 0 op_sel_hi:[0,1,0]
	v_pk_fma_f32 v[38:39], v[74:75], v[166:167], v[38:39] op_sel:[0,1,0] neg_lo:[0,0,1] neg_hi:[0,0,1]
	v_mov_b32_e32 v42, v169
	v_pk_fma_f32 v[60:61], v[60:61], v[198:199], v[38:39] op_sel:[0,1,0]
	v_pk_mul_f32 v[38:39], v[172:173], v[160:161] op_sel_hi:[0,1]
	v_pk_fma_f32 v[38:39], v[74:75], v[168:169], v[38:39] op_sel_hi:[1,0,1] neg_lo:[0,0,1] neg_hi:[0,0,1]
	v_pk_mul_f32 v[40:41], v[172:173], v[160:161] op_sel:[1,0]
	v_pk_fma_f32 v[2:3], v[158:159], v[66:67], v[2:3] op_sel_hi:[0,1,1]
	v_pk_fma_f32 v[46:47], v[46:47], v[200:201], v[38:39] op_sel_hi:[1,0,1]
	v_pk_fma_f32 v[40:41], v[74:75], v[42:43], v[40:41] op_sel_hi:[1,0,1] neg_lo:[0,0,1] neg_hi:[0,0,1]
	v_pk_fma_f32 v[2:3], v[152:153], v[62:63], v[2:3] op_sel_hi:[0,1,1]
	v_pk_fma_f32 v[36:37], v[152:153], v[60:61], v[36:37] op_sel:[1,0,0]
	v_pk_fma_f32 v[44:45], v[44:45], v[200:201], v[40:41] op_sel:[0,1,0]
	v_mov_b32_e32 v38, v155
	v_pk_fma_f32 v[2:3], v[154:155], v[46:47], v[2:3] op_sel_hi:[0,1,1]
	v_pk_fma_f32 v[36:37], v[38:39], v[44:45], v[36:37] op_sel_hi:[0,1,1]
	v_pk_add_f32 v[2:3], v[2:3], v[36:37]
	s_nop 1
	v_add_f32_dpp v2, v2, v2 quad_perm:[1,0,3,2] row_mask:0xf bank_mask:0xf bound_ctrl:1
	v_add_f32_dpp v3, v3, v3 quad_perm:[1,0,3,2] row_mask:0xf bank_mask:0xf bound_ctrl:1
	s_nop 0
	v_add_f32_dpp v2, v2, v2 quad_perm:[2,3,0,1] row_mask:0xf bank_mask:0xf bound_ctrl:1
	v_add_f32_dpp v3, v3, v3 quad_perm:[2,3,0,1] row_mask:0xf bank_mask:0xf bound_ctrl:1
	s_nop 0
	v_mov_b32_dpp v36, v2 row_half_mirror row_mask:0xf bank_mask:0xf bound_ctrl:1
	v_mov_b32_dpp v37, v3 row_half_mirror row_mask:0xf bank_mask:0xf bound_ctrl:1
	s_and_saveexec_b64 s[20:21], s[14:15]
	s_cbranch_execz .LBB0_575
	v_pk_add_f32 v[2:3], v[2:3], v[36:37]
	ds_write_b64 v72, v[2:3] offset:52992
	s_branch .LBB0_575
